# GEMM tile loops: first K iteration peeled with C=0 MFMAs, per-tile accumulator zeroing removed (5 loops); prologue fill reorder kept
# speedup vs baseline: 1.0135x; 1.0074x over previous
; #define PG8_STAGE(bufoff, gbase, voff) do { _Pragma("unroll") for (int _i = 0; _i < 2; ++_i) \
;         __builtin_amdgcn_global_load_lds((const unsigned*)((const char*)(gbase) + (voff)[_i]), (LAS unsigned*)(lds + (bufoff) + ldsw + _i * 8192), 16, 0, 0); } while (0)
; #define PG8_LDA(dst, b, h) do { _Pragma("unroll") for (int m = 0; m < 4; ++m) _Pragma("unroll") for (int k = 0; k < 2; ++k) dst[m][k] = *(const LAS bf16x8*)(lds + PG8_SA(b, h) + aoff + m * 2048 + k * 1024); } while (0)
; #define PG8_LDB(dst, b, h) do { _Pragma("unroll") for (int n = 0; n < 2; ++n) _Pragma("unroll") for (int k = 0; k < 2; ++k) dst[n][k] = *(const LAS bf16x8*)(lds + PG8_SB(b, h) + boff + n * 2048 + k * 1024); } while (0)
; #define PG8_MMA(ai, bj, At, Bt) do { __builtin_amdgcn_s_setprio(1); _Pragma("unroll") for (int m = 0; m < 4; ++m) _Pragma("unroll") for (int n = 0; n < 2; ++n) _Pragma("unroll") for (int k = 0; k < 2; ++k) \
;         acc[ai][bj][m][n] = __builtin_amdgcn_mfma_f32_16x16x32_bf16(Bt[n][k], At[m][k], acc[ai][bj][m][n], 0, 0, 0); __builtin_amdgcn_s_setprio(0); } while (0)
; template <class Epi, bool HALFM = false>
; DI void gemm_phase(LAS unsigned char* lds, const Gemm g, const StaticOrder& S, const Epi& E) {
;     ...
; #pragma unroll
;     for (int a = 0; a < 2; ++a)
; #pragma unroll
;         for (int b = 0; b < 2; ++b)
; #pragma unroll
;             for (int m = 0; m < 4; ++m)
; #pragma unroll
;                 for (int n = 0; n < 2; ++n) acc[a][b][m][n] = (f32x4){0.f, 0.f, 0.f, 0.f};
;     ...
;             const bool last = (t == nt - 2);
;             const char* a1 = cA + (size_t)(t + 1) * kstep;
;             const char* a2 = last ? nA : cA + (size_t)(t + 2) * kstep; const char* b2 = last ? nB : cB + (size_t)(t + 2) * kstep;
;             const char* a3 = a2 + kstep; const char* b3 = b2 + kstep;
;             PG8_LDB(B0, 0, 0); PG8_LDB(B1, 0, 1); PG8_SCHED; PG8_LDA(At, 0, 0); PG8_STAGE(PG8_SA(1, 1), a1 + hstepA, voffA);
;             PG8_WAIT_V(8); PG8_WAIT_L(0); PG8_BAR; PG8_MMA(0, 0, At, B0); PG8_MMA(0, 1, At, B1); PG8_BAR; PG8_SCHED;
;             if constexpr (!HALFM) PG8_LDA(At, 0, 1);
;             PG8_STAGE(PG8_SB(0, 0), b2, voffB); PG8_STAGE(PG8_SB(0, 1), b2 + hstepB, voffB); PG8_STAGE(PG8_SA(0, 0), a2, voffA);
;             PG8_WAIT_V(8); PG8_WAIT_L(0); PG8_BAR; if constexpr (!HALFM) { PG8_MMA(1, 0, At, B0); PG8_MMA(1, 1, At, B1); } PG8_BAR; PG8_SCHED;
.LBB0_291:
	s_add_u32 s10, s10, 0x80
	s_addc_u32 s11, s11, 0
	s_add_u32 s4, s12, 0x100
	s_addc_u32 s5, s13, 0
	s_mov_b32 s12, 0
	s_waitcnt vmcnt(0)
	v_readlane_b32 s48, v254, 24
	v_readlane_b32 s50, v254, 20
	v_readlane_b32 s49, v254, 25
	v_readlane_b32 s51, v254, 21
	s_add_i32 s26, s12, 2
	s_add_u32 s27, s10, 0x80
	s_addc_u32 s13, s11, 0
	s_add_i32 s33, s90, 0x100
	s_cmp_eq_u32 s49, s12
	s_cselect_b32 s13, s7, s13
	s_cselect_b32 s12, s6, s27
	s_cselect_b32 s47, s25, s5
	s_cselect_b32 s46, s24, s4
	s_add_i32 s27, s91, 0x100
	v_add_u32_e32 v142, s33, v244
	v_add_u32_e32 v158, s27, v244
	ds_read_b128 v[130:133], v142
	ds_read_b128 v[134:137], v142 offset:1024
	ds_read_b128 v[138:141], v142 offset:2048
	ds_read_b128 v[142:145], v142 offset:3072
	ds_read_b128 v[146:149], v158
	ds_read_b128 v[150:153], v158 offset:1024
	ds_read_b128 v[154:157], v158 offset:2048
	ds_read_b128 v[158:161], v158 offset:3072
	v_lshl_add_u64 v[194:195], s[10:11], 0, v[214:215]
	s_add_i32 m0, s35, 0xc000
	ds_read_b128 v[162:165], v245
	ds_read_b128 v[166:169], v245 offset:1024
	ds_read_b128 v[170:173], v245 offset:2048
	ds_read_b128 v[174:177], v245 offset:3072
	ds_read_b128 v[178:181], v245 offset:4096
	ds_read_b128 v[182:185], v245 offset:5120
	ds_read_b128 v[186:189], v245 offset:6144
	ds_read_b128 v[190:193], v245 offset:7168
	global_load_lds_dwordx4 v[194:195], off
	v_lshl_add_u64 v[194:195], s[10:11], 0, v[216:217]
	s_add_i32 m0, s35, 0xe000
	s_nop 0
	global_load_lds_dwordx4 v[194:195], off
	s_waitcnt vmcnt(8)
	s_waitcnt lgkmcnt(0)
	s_barrier
	s_setprio 1
	s_waitcnt lgkmcnt(0)
	v_mfma_f32_16x16x32_bf16 v[126:129], v[130:133], v[162:165], 0
	v_mfma_f32_16x16x32_bf16 v[122:125], v[138:141], v[162:165], 0
	v_mfma_f32_16x16x32_bf16 v[110:113], v[130:133], v[170:173], 0
	v_mfma_f32_16x16x32_bf16 v[106:109], v[138:141], v[170:173], 0
	v_mfma_f32_16x16x32_bf16 v[94:97], v[130:133], v[178:181], 0
	v_mfma_f32_16x16x32_bf16 v[90:93], v[138:141], v[178:181], 0
	v_mfma_f32_16x16x32_bf16 v[78:81], v[130:133], v[186:189], 0
	v_mfma_f32_16x16x32_bf16 v[74:77], v[138:141], v[186:189], 0
	v_mfma_f32_16x16x32_bf16 v[126:129], v[134:137], v[166:169], v[126:129]
	v_mfma_f32_16x16x32_bf16 v[122:125], v[142:145], v[166:169], v[122:125]
	v_mfma_f32_16x16x32_bf16 v[110:113], v[134:137], v[174:177], v[110:113]
	v_mfma_f32_16x16x32_bf16 v[106:109], v[142:145], v[174:177], v[106:109]
	v_mfma_f32_16x16x32_bf16 v[94:97], v[134:137], v[182:185], v[94:97]
	v_mfma_f32_16x16x32_bf16 v[90:93], v[142:145], v[182:185], v[90:93]
	v_mfma_f32_16x16x32_bf16 v[78:81], v[134:137], v[190:193], v[78:81]
	v_mfma_f32_16x16x32_bf16 v[74:77], v[142:145], v[190:193], v[74:77]
	s_setprio 0
	s_setprio 1
	v_mfma_f32_16x16x32_bf16 v[118:121], v[146:149], v[162:165], 0
	v_mfma_f32_16x16x32_bf16 v[114:117], v[154:157], v[162:165], 0
	v_mfma_f32_16x16x32_bf16 v[102:105], v[146:149], v[170:173], 0
	v_mfma_f32_16x16x32_bf16 v[98:101], v[154:157], v[170:173], 0
	v_mfma_f32_16x16x32_bf16 v[86:89], v[146:149], v[178:181], 0
	v_mfma_f32_16x16x32_bf16 v[82:85], v[154:157], v[178:181], 0
	v_mfma_f32_16x16x32_bf16 v[70:73], v[146:149], v[186:189], 0
	v_mfma_f32_16x16x32_bf16 v[66:69], v[154:157], v[186:189], 0
	v_mfma_f32_16x16x32_bf16 v[118:121], v[150:153], v[166:169], v[118:121]
	v_mfma_f32_16x16x32_bf16 v[114:117], v[158:161], v[166:169], v[114:117]
	v_mfma_f32_16x16x32_bf16 v[102:105], v[150:153], v[174:177], v[102:105]
	v_mfma_f32_16x16x32_bf16 v[98:101], v[158:161], v[174:177], v[98:101]
	v_mfma_f32_16x16x32_bf16 v[86:89], v[150:153], v[182:185], v[86:89]
	v_mfma_f32_16x16x32_bf16 v[82:85], v[158:161], v[182:185], v[82:85]
	v_mfma_f32_16x16x32_bf16 v[70:73], v[150:153], v[190:193], v[70:73]
	v_mfma_f32_16x16x32_bf16 v[66:69], v[158:161], v[190:193], v[66:69]
	s_setprio 0
	s_barrier
	s_add_i32 s33, s33, s28
	v_lshl_add_u64 v[194:195], s[46:47], 0, v[0:1]
	s_mov_b32 m0, s33
	ds_read_b128 v[162:165], v245 offset:16384
	ds_read_b128 v[166:169], v245 offset:17408
	ds_read_b128 v[170:173], v245 offset:18432
	ds_read_b128 v[174:177], v245 offset:19456
	ds_read_b128 v[178:181], v245 offset:20480
	ds_read_b128 v[182:185], v245 offset:21504
	ds_read_b128 v[186:189], v245 offset:22528
	ds_read_b128 v[190:193], v245 offset:23552
	global_load_lds_dwordx4 v[194:195], off
	s_add_i32 m0, s33, 0x2000
	v_lshl_add_u64 v[196:197], s[46:47], 0, v[208:209]
	s_add_u32 s46, s46, s50
	s_addc_u32 s47, s47, 0
	s_add_i32 s27, s27, s28
	global_load_lds_dwordx4 v[196:197], off
	v_lshl_add_u64 v[198:199], s[46:47], 0, v[0:1]
	s_mov_b32 m0, s27
	v_lshl_add_u64 v[200:201], s[46:47], 0, v[208:209]
	global_load_lds_dwordx4 v[198:199], off
	s_add_i32 m0, s27, 0x2000
	v_lshl_add_u64 v[218:219], s[12:13], 0, v[212:213]
	global_load_lds_dwordx4 v[200:201], off
	s_mov_b32 m0, s35
	v_lshl_add_u64 v[220:221], s[12:13], 0, v[210:211]
	global_load_lds_dwordx4 v[218:219], off
	s_mov_b32 m0, s36
	s_nop 0
	global_load_lds_dwordx4 v[220:221], off
	s_waitcnt vmcnt(8)
	s_waitcnt lgkmcnt(0)
	s_barrier
; #define PG8_STAGE(bufoff, gbase, voff) do { _Pragma("unroll") for (int _i = 0; _i < 2; ++_i) \
;         __builtin_amdgcn_global_load_lds((const unsigned*)((const char*)(gbase) + (voff)[_i]), (LAS unsigned*)(lds + (bufoff) + ldsw + _i * 8192), 16, 0, 0); } while (0)
; #define PG8_LDA(dst, b, h) do { _Pragma("unroll") for (int m = 0; m < 4; ++m) _Pragma("unroll") for (int k = 0; k < 2; ++k) dst[m][k] = *(const LAS bf16x8*)(lds + PG8_SA(b, h) + aoff + m * 2048 + k * 1024); } while (0)
; #define PG8_LDB(dst, b, h) do { _Pragma("unroll") for (int n = 0; n < 2; ++n) _Pragma("unroll") for (int k = 0; k < 2; ++k) dst[n][k] = *(const LAS bf16x8*)(lds + PG8_SB(b, h) + boff + n * 2048 + k * 1024); } while (0)
; #define PG8_MMA(ai, bj, At, Bt) do { __builtin_amdgcn_s_setprio(1); _Pragma("unroll") for (int m = 0; m < 4; ++m) _Pragma("unroll") for (int n = 0; n < 2; ++n) _Pragma("unroll") for (int k = 0; k < 2; ++k) \
;         acc[ai][bj][m][n] = __builtin_amdgcn_mfma_f32_16x16x32_bf16(Bt[n][k], At[m][k], acc[ai][bj][m][n], 0, 0, 0); __builtin_amdgcn_s_setprio(0); } while (0)
; #define PG8_WAIT_V(n) asm volatile("s_waitcnt vmcnt(" #n ")" ::: "memory")
; #define PG8_WAIT_L(n) asm volatile("s_waitcnt lgkmcnt(" #n ")" ::: "memory")
; #define PG8_BAR __builtin_amdgcn_s_barrier()
; #define PG8_SCHED __builtin_amdgcn_sched_barrier(0)
; template <class Epi, bool HALFM = false>
; DI void gemm_phase(LAS unsigned char* lds, const Gemm g, const StaticOrder& S, const Epi& E) {
;     ...
;             PG8_WAIT_V(8); PG8_WAIT_L(0); PG8_BAR; if constexpr (!HALFM) { PG8_MMA(1, 0, At, B0); PG8_MMA(1, 1, At, B1); } PG8_BAR; PG8_SCHED;
;             PG8_LDB(B0, 1, 0); PG8_LDB(B1, 1, 1); PG8_SCHED; PG8_LDA(At, 1, 0); PG8_STAGE(PG8_SA(0, 1), a2 + hstepA, voffA);
;             PG8_WAIT_V(8); PG8_WAIT_L(0); PG8_BAR; PG8_MMA(0, 0, At, B0); PG8_MMA(0, 1, At, B1); PG8_BAR; PG8_SCHED;
	s_setprio 1
	s_waitcnt lgkmcnt(0)
	v_mfma_f32_16x16x32_bf16 v[62:65], v[130:133], v[162:165], 0
	v_mfma_f32_16x16x32_bf16 v[58:61], v[138:141], v[162:165], 0
	v_mfma_f32_16x16x32_bf16 v[46:49], v[130:133], v[170:173], 0
	v_mfma_f32_16x16x32_bf16 v[42:45], v[138:141], v[170:173], 0
	v_mfma_f32_16x16x32_bf16 v[30:33], v[130:133], v[178:181], 0
	v_mfma_f32_16x16x32_bf16 v[26:29], v[138:141], v[178:181], 0
	v_mfma_f32_16x16x32_bf16 v[14:17], v[130:133], v[186:189], 0
	v_mfma_f32_16x16x32_bf16 v[10:13], v[138:141], v[186:189], 0
	v_mfma_f32_16x16x32_bf16 v[62:65], v[134:137], v[166:169], v[62:65]
	v_mfma_f32_16x16x32_bf16 v[58:61], v[142:145], v[166:169], v[58:61]
	v_mfma_f32_16x16x32_bf16 v[46:49], v[134:137], v[174:177], v[46:49]
	v_mfma_f32_16x16x32_bf16 v[42:45], v[142:145], v[174:177], v[42:45]
	v_mfma_f32_16x16x32_bf16 v[30:33], v[134:137], v[182:185], v[30:33]
	v_mfma_f32_16x16x32_bf16 v[26:29], v[142:145], v[182:185], v[26:29]
	v_mfma_f32_16x16x32_bf16 v[14:17], v[134:137], v[190:193], v[14:17]
	v_mfma_f32_16x16x32_bf16 v[10:13], v[142:145], v[190:193], v[10:13]
	s_setprio 0
	s_setprio 1
	v_mfma_f32_16x16x32_bf16 v[54:57], v[146:149], v[162:165], 0
	v_mfma_f32_16x16x32_bf16 v[50:53], v[154:157], v[162:165], 0
	v_mfma_f32_16x16x32_bf16 v[38:41], v[146:149], v[170:173], 0
	v_mfma_f32_16x16x32_bf16 v[34:37], v[154:157], v[170:173], 0
	v_mfma_f32_16x16x32_bf16 v[22:25], v[146:149], v[178:181], 0
	v_mfma_f32_16x16x32_bf16 v[18:21], v[154:157], v[178:181], 0
	v_mfma_f32_16x16x32_bf16 v[6:9], v[146:149], v[186:189], 0
	v_mfma_f32_16x16x32_bf16 v[2:5], v[154:157], v[186:189], 0
	v_mfma_f32_16x16x32_bf16 v[54:57], v[150:153], v[166:169], v[54:57]
	v_mfma_f32_16x16x32_bf16 v[50:53], v[158:161], v[166:169], v[50:53]
	v_mfma_f32_16x16x32_bf16 v[38:41], v[150:153], v[174:177], v[38:41]
	v_mfma_f32_16x16x32_bf16 v[34:37], v[158:161], v[174:177], v[34:37]
	v_mfma_f32_16x16x32_bf16 v[22:25], v[150:153], v[182:185], v[22:25]
	v_mfma_f32_16x16x32_bf16 v[18:21], v[158:161], v[182:185], v[18:21]
	v_mfma_f32_16x16x32_bf16 v[6:9], v[150:153], v[190:193], v[6:9]
	v_mfma_f32_16x16x32_bf16 v[2:5], v[158:161], v[190:193], v[2:5]
	s_setprio 0
	s_barrier
	s_add_i32 s27, s92, 0x100
	s_add_i32 s33, s93, 0x100
	v_add_u32_e32 v142, s27, v244
	v_add_u32_e32 v158, s33, v244
	ds_read_b128 v[130:133], v142
	ds_read_b128 v[134:137], v142 offset:1024
	ds_read_b128 v[138:141], v142 offset:2048
	ds_read_b128 v[142:145], v142 offset:3072
	ds_read_b128 v[146:149], v158
	ds_read_b128 v[150:153], v158 offset:1024
	ds_read_b128 v[154:157], v158 offset:2048
	ds_read_b128 v[158:161], v158 offset:3072
	s_add_u32 s12, s12, s50
	s_addc_u32 s13, s13, 0
	s_mov_b32 m0, s37
	v_lshl_add_u64 v[222:223], s[12:13], 0, v[212:213]
	ds_read_b128 v[162:165], v245 offset:32768
	ds_read_b128 v[166:169], v245 offset:33792
	ds_read_b128 v[170:173], v245 offset:34816
	ds_read_b128 v[174:177], v245 offset:35840
	ds_read_b128 v[178:181], v245 offset:36864
	ds_read_b128 v[182:185], v245 offset:37888
	ds_read_b128 v[186:189], v245 offset:38912
	ds_read_b128 v[190:193], v245 offset:39936
	global_load_lds_dwordx4 v[222:223], off
	v_lshl_add_u64 v[222:223], s[12:13], 0, v[210:211]
	s_mov_b32 m0, s38
	s_nop 0
	global_load_lds_dwordx4 v[222:223], off
	s_waitcnt vmcnt(8)
	s_waitcnt lgkmcnt(0)
	s_barrier
	s_setprio 1
	s_waitcnt lgkmcnt(0)
	v_mfma_f32_16x16x32_bf16 v[126:129], v[130:133], v[162:165], v[126:129]
	v_mfma_f32_16x16x32_bf16 v[122:125], v[138:141], v[162:165], v[122:125]
	v_mfma_f32_16x16x32_bf16 v[110:113], v[130:133], v[170:173], v[110:113]
	v_mfma_f32_16x16x32_bf16 v[106:109], v[138:141], v[170:173], v[106:109]
	v_mfma_f32_16x16x32_bf16 v[94:97], v[130:133], v[178:181], v[94:97]
	v_mfma_f32_16x16x32_bf16 v[90:93], v[138:141], v[178:181], v[90:93]
	v_mfma_f32_16x16x32_bf16 v[78:81], v[130:133], v[186:189], v[78:81]
	v_mfma_f32_16x16x32_bf16 v[74:77], v[138:141], v[186:189], v[74:77]
	v_mfma_f32_16x16x32_bf16 v[126:129], v[134:137], v[166:169], v[126:129]
	v_mfma_f32_16x16x32_bf16 v[122:125], v[142:145], v[166:169], v[122:125]
	v_mfma_f32_16x16x32_bf16 v[110:113], v[134:137], v[174:177], v[110:113]
	v_mfma_f32_16x16x32_bf16 v[106:109], v[142:145], v[174:177], v[106:109]
	v_mfma_f32_16x16x32_bf16 v[94:97], v[134:137], v[182:185], v[94:97]
	v_mfma_f32_16x16x32_bf16 v[90:93], v[142:145], v[182:185], v[90:93]
	v_mfma_f32_16x16x32_bf16 v[78:81], v[134:137], v[190:193], v[78:81]
	v_mfma_f32_16x16x32_bf16 v[74:77], v[142:145], v[190:193], v[74:77]
	s_setprio 0
	s_setprio 1
	v_mfma_f32_16x16x32_bf16 v[118:121], v[146:149], v[162:165], v[118:121]
	v_mfma_f32_16x16x32_bf16 v[114:117], v[154:157], v[162:165], v[114:117]
	v_mfma_f32_16x16x32_bf16 v[102:105], v[146:149], v[170:173], v[102:105]
	v_mfma_f32_16x16x32_bf16 v[98:101], v[154:157], v[170:173], v[98:101]
	v_mfma_f32_16x16x32_bf16 v[86:89], v[146:149], v[178:181], v[86:89]
	v_mfma_f32_16x16x32_bf16 v[82:85], v[154:157], v[178:181], v[82:85]
	v_mfma_f32_16x16x32_bf16 v[70:73], v[146:149], v[186:189], v[70:73]
	v_mfma_f32_16x16x32_bf16 v[66:69], v[154:157], v[186:189], v[66:69]
	v_mfma_f32_16x16x32_bf16 v[118:121], v[150:153], v[166:169], v[118:121]
	v_mfma_f32_16x16x32_bf16 v[114:117], v[158:161], v[166:169], v[114:117]
	v_mfma_f32_16x16x32_bf16 v[102:105], v[150:153], v[174:177], v[102:105]
	v_mfma_f32_16x16x32_bf16 v[98:101], v[158:161], v[174:177], v[98:101]
	v_mfma_f32_16x16x32_bf16 v[86:89], v[150:153], v[182:185], v[86:89]
	v_mfma_f32_16x16x32_bf16 v[82:85], v[158:161], v[182:185], v[82:85]
	v_mfma_f32_16x16x32_bf16 v[70:73], v[150:153], v[190:193], v[70:73]
	v_mfma_f32_16x16x32_bf16 v[66:69], v[158:161], v[190:193], v[66:69]
	s_setprio 0
	s_barrier
; #define PG8_STAGE(bufoff, gbase, voff) do { _Pragma("unroll") for (int _i = 0; _i < 2; ++_i) \
;         __builtin_amdgcn_global_load_lds((const unsigned*)((const char*)(gbase) + (voff)[_i]), (LAS unsigned*)(lds + (bufoff) + ldsw + _i * 8192), 16, 0, 0); } while (0)
; #define PG8_LDA(dst, b, h) do { _Pragma("unroll") for (int m = 0; m < 4; ++m) _Pragma("unroll") for (int k = 0; k < 2; ++k) dst[m][k] = *(const LAS bf16x8*)(lds + PG8_SA(b, h) + aoff + m * 2048 + k * 1024); } while (0)
; #define PG8_MMA(ai, bj, At, Bt) do { __builtin_amdgcn_s_setprio(1); _Pragma("unroll") for (int m = 0; m < 4; ++m) _Pragma("unroll") for (int n = 0; n < 2; ++n) _Pragma("unroll") for (int k = 0; k < 2; ++k) \
;         acc[ai][bj][m][n] = __builtin_amdgcn_mfma_f32_16x16x32_bf16(Bt[n][k], At[m][k], acc[ai][bj][m][n], 0, 0, 0); __builtin_amdgcn_s_setprio(0); } while (0)
; #define PG8_WAIT_V(n) asm volatile("s_waitcnt vmcnt(" #n ")" ::: "memory")
; #define PG8_WAIT_L(n) asm volatile("s_waitcnt lgkmcnt(" #n ")" ::: "memory")
; #define PG8_BAR __builtin_amdgcn_s_barrier()
; #define PG8_SCHED __builtin_amdgcn_sched_barrier(0)
; template <class Epi, bool HALFM = false>
; DI void gemm_phase(LAS unsigned char* lds, const Gemm g, const StaticOrder& S, const Epi& E) {
;     ...
;             if constexpr (!HALFM) PG8_LDA(At, 1, 1);
;             PG8_STAGE(PG8_SB(1, 0), b3, voffB); PG8_STAGE(PG8_SB(1, 1), b3 + hstepB, voffB); PG8_STAGE(PG8_SA(1, 0), a3, voffA);
;             PG8_WAIT_V(8); PG8_WAIT_L(0); PG8_BAR; if constexpr (!HALFM) { PG8_MMA(1, 0, At, B0); PG8_MMA(1, 1, At, B1); } PG8_BAR; PG8_SCHED;
	s_add_i32 s12, s27, s28
	v_lshl_add_u64 v[194:195], v[194:195], 0, s[2:3]
	s_mov_b32 m0, s12
	ds_read_b128 v[162:165], v245 offset:49152
	ds_read_b128 v[166:169], v245 offset:50176
	ds_read_b128 v[170:173], v245 offset:51200
	ds_read_b128 v[174:177], v245 offset:52224
	ds_read_b128 v[178:181], v245 offset:53248
	ds_read_b128 v[182:185], v245 offset:54272
	ds_read_b128 v[186:189], v245 offset:55296
	ds_read_b128 v[190:193], v245 offset:56320
	global_load_lds_dwordx4 v[194:195], off
	v_lshl_add_u64 v[194:195], v[196:197], 0, s[2:3]
	s_add_i32 m0, s12, 0x2000
	s_add_i32 s12, s33, s28
	global_load_lds_dwordx4 v[194:195], off
	v_lshl_add_u64 v[194:195], v[198:199], 0, s[2:3]
	s_mov_b32 m0, s12
	s_nop 0
	global_load_lds_dwordx4 v[194:195], off
	v_lshl_add_u64 v[194:195], v[200:201], 0, s[2:3]
	s_add_i32 m0, s12, 0x2000
	s_nop 0
	global_load_lds_dwordx4 v[194:195], off
	v_lshl_add_u64 v[194:195], v[218:219], 0, s[2:3]
	s_mov_b32 m0, s41
	s_nop 0
	global_load_lds_dwordx4 v[194:195], off
	v_lshl_add_u64 v[194:195], v[220:221], 0, s[2:3]
	s_mov_b32 m0, s42
	s_nop 0
	global_load_lds_dwordx4 v[194:195], off
	s_waitcnt vmcnt(8)
	s_waitcnt lgkmcnt(0)
	s_barrier
	s_setprio 1
	s_waitcnt lgkmcnt(0)
	v_mfma_f32_16x16x32_bf16 v[62:65], v[130:133], v[162:165], v[62:65]
	v_mfma_f32_16x16x32_bf16 v[58:61], v[138:141], v[162:165], v[58:61]
	v_mfma_f32_16x16x32_bf16 v[46:49], v[130:133], v[170:173], v[46:49]
	v_mfma_f32_16x16x32_bf16 v[42:45], v[138:141], v[170:173], v[42:45]
	v_mfma_f32_16x16x32_bf16 v[30:33], v[130:133], v[178:181], v[30:33]
	v_mfma_f32_16x16x32_bf16 v[26:29], v[138:141], v[178:181], v[26:29]
	v_mfma_f32_16x16x32_bf16 v[14:17], v[130:133], v[186:189], v[14:17]
	v_mfma_f32_16x16x32_bf16 v[10:13], v[138:141], v[186:189], v[10:13]
	v_mfma_f32_16x16x32_bf16 v[62:65], v[134:137], v[166:169], v[62:65]
	v_mfma_f32_16x16x32_bf16 v[58:61], v[142:145], v[166:169], v[58:61]
	v_mfma_f32_16x16x32_bf16 v[46:49], v[134:137], v[174:177], v[46:49]
	v_mfma_f32_16x16x32_bf16 v[42:45], v[142:145], v[174:177], v[42:45]
	v_mfma_f32_16x16x32_bf16 v[30:33], v[134:137], v[182:185], v[30:33]
	v_mfma_f32_16x16x32_bf16 v[26:29], v[142:145], v[182:185], v[26:29]
	v_mfma_f32_16x16x32_bf16 v[14:17], v[134:137], v[190:193], v[14:17]
	v_mfma_f32_16x16x32_bf16 v[10:13], v[142:145], v[190:193], v[10:13]
	s_setprio 0
	s_setprio 1
	v_mfma_f32_16x16x32_bf16 v[54:57], v[146:149], v[162:165], v[54:57]
	v_mfma_f32_16x16x32_bf16 v[50:53], v[154:157], v[162:165], v[50:53]
	v_mfma_f32_16x16x32_bf16 v[38:41], v[146:149], v[170:173], v[38:41]
	v_mfma_f32_16x16x32_bf16 v[34:37], v[154:157], v[170:173], v[34:37]
	v_mfma_f32_16x16x32_bf16 v[22:25], v[146:149], v[178:181], v[22:25]
	v_mfma_f32_16x16x32_bf16 v[18:21], v[154:157], v[178:181], v[18:21]
	v_mfma_f32_16x16x32_bf16 v[6:9], v[146:149], v[186:189], v[6:9]
	v_mfma_f32_16x16x32_bf16 v[2:5], v[154:157], v[186:189], v[2:5]
	v_mfma_f32_16x16x32_bf16 v[54:57], v[150:153], v[166:169], v[54:57]
	v_mfma_f32_16x16x32_bf16 v[50:53], v[158:161], v[166:169], v[50:53]
	v_mfma_f32_16x16x32_bf16 v[38:41], v[150:153], v[174:177], v[38:41]
	v_mfma_f32_16x16x32_bf16 v[34:37], v[158:161], v[174:177], v[34:37]
	v_mfma_f32_16x16x32_bf16 v[22:25], v[150:153], v[182:185], v[22:25]
	v_mfma_f32_16x16x32_bf16 v[18:21], v[158:161], v[182:185], v[18:21]
	v_mfma_f32_16x16x32_bf16 v[6:9], v[150:153], v[190:193], v[6:9]
	v_mfma_f32_16x16x32_bf16 v[2:5], v[158:161], v[190:193], v[2:5]
	s_setprio 0
	s_barrier
	s_add_u32 s10, s10, 0x100
	s_addc_u32 s11, s11, 0
	s_add_u32 s4, s4, 0x100
	s_addc_u32 s5, s5, 0
	s_cmp_ge_u32 s26, s48
	s_mov_b32 s12, s26

; #define PG8_STAGE(bufoff, gbase, voff) do { _Pragma("unroll") for (int _i = 0; _i < 2; ++_i) \
;         __builtin_amdgcn_global_load_lds((const unsigned*)((const char*)(gbase) + (voff)[_i]), (LAS unsigned*)(lds + (bufoff) + ldsw + _i * 8192), 16, 0, 0); } while (0)
; #define PG8_LDA(dst, b, h) do { _Pragma("unroll") for (int m = 0; m < 4; ++m) _Pragma("unroll") for (int k = 0; k < 2; ++k) dst[m][k] = *(const LAS bf16x8*)(lds + PG8_SA(b, h) + aoff + m * 2048 + k * 1024); } while (0)
; #define PG8_LDB(dst, b, h) do { _Pragma("unroll") for (int n = 0; n < 2; ++n) _Pragma("unroll") for (int k = 0; k < 2; ++k) dst[n][k] = *(const LAS bf16x8*)(lds + PG8_SB(b, h) + boff + n * 2048 + k * 1024); } while (0)
; #define PG8_MMA(ai, bj, At, Bt) do { __builtin_amdgcn_s_setprio(1); _Pragma("unroll") for (int m = 0; m < 4; ++m) _Pragma("unroll") for (int n = 0; n < 2; ++n) _Pragma("unroll") for (int k = 0; k < 2; ++k) \
;         acc[ai][bj][m][n] = __builtin_amdgcn_mfma_f32_16x16x32_bf16(Bt[n][k], At[m][k], acc[ai][bj][m][n], 0, 0, 0); __builtin_amdgcn_s_setprio(0); } while (0)
; template <class Epi, bool HALFM = false>
; DI void gemm_phase(LAS unsigned char* lds, const Gemm g, const StaticOrder& S, const Epi& E) {
;     ...
; #pragma unroll
;     for (int a = 0; a < 2; ++a)
; #pragma unroll
;         for (int b = 0; b < 2; ++b)
; #pragma unroll
;             for (int m = 0; m < 4; ++m)
; #pragma unroll
;                 for (int n = 0; n < 2; ++n) acc[a][b][m][n] = (f32x4){0.f, 0.f, 0.f, 0.f};
;     ...
;             const bool last = (t == nt - 2);
;             const char* a1 = cA + (size_t)(t + 1) * kstep;
;             const char* a2 = last ? nA : cA + (size_t)(t + 2) * kstep; const char* b2 = last ? nB : cB + (size_t)(t + 2) * kstep;
;             const char* a3 = a2 + kstep; const char* b3 = b2 + kstep;
;             PG8_LDB(B0, 0, 0); PG8_LDB(B1, 0, 1); PG8_SCHED; PG8_LDA(At, 0, 0); PG8_STAGE(PG8_SA(1, 1), a1 + hstepA, voffA);
;             PG8_WAIT_V(8); PG8_WAIT_L(0); PG8_BAR; PG8_MMA(0, 0, At, B0); PG8_MMA(0, 1, At, B1); PG8_BAR; PG8_SCHED;
;             if constexpr (!HALFM) PG8_LDA(At, 0, 1);
;             PG8_STAGE(PG8_SB(0, 0), b2, voffB); PG8_STAGE(PG8_SB(0, 1), b2 + hstepB, voffB); PG8_STAGE(PG8_SA(0, 0), a2, voffA);
;             PG8_WAIT_V(8); PG8_WAIT_L(0); PG8_BAR; if constexpr (!HALFM) { PG8_MMA(1, 0, At, B0); PG8_MMA(1, 1, At, B1); } PG8_BAR; PG8_SCHED;
.LBB0_364:
	s_add_u32 s4, s12, 0x100
	s_addc_u32 s5, s13, 0
	s_mov_b32 s33, -2
	s_add_u32 s6, s10, 0x100
	s_addc_u32 s7, s11, 0
	s_add_i32 s38, s90, 0x100
	s_cmp_eq_u32 s33, 2
	s_cselect_b32 s15, s35, s7
	s_cselect_b32 s14, s34, s6
	s_cselect_b32 s13, s37, s5
	s_cselect_b32 s12, s36, s4
	s_add_i32 s39, s91, 0x100
	v_add_u32_e32 v154, s38, v148
	v_add_u32_e32 v170, s39, v148
	ds_read_b128 v[140:143], v154
	ds_read_b128 v[144:147], v154 offset:1024
	ds_read_b128 v[150:153], v154 offset:2048
	ds_read_b128 v[154:157], v154 offset:3072
	ds_read_b128 v[158:161], v170
	ds_read_b128 v[162:165], v170 offset:1024
	ds_read_b128 v[166:169], v170 offset:2048
	ds_read_b128 v[170:173], v170 offset:3072
	v_lshl_add_u64 v[212:213], s[10:11], 0, v[136:137]
	s_add_i32 m0, s45, 0xc000
	ds_read_b128 v[174:177], v149
	ds_read_b128 v[178:181], v149 offset:1024
	ds_read_b128 v[182:185], v149 offset:2048
	ds_read_b128 v[186:189], v149 offset:3072
	ds_read_b128 v[190:193], v149 offset:4096
	ds_read_b128 v[194:197], v149 offset:5120
	ds_read_b128 v[198:201], v149 offset:6144
	ds_read_b128 v[208:211], v149 offset:7168
	global_load_lds_dwordx4 v[212:213], off
	v_lshl_add_u64 v[212:213], s[10:11], 0, v[138:139]
	s_add_i32 m0, s45, 0xe000
	s_nop 0
	global_load_lds_dwordx4 v[212:213], off
	s_waitcnt vmcnt(8)
	s_waitcnt lgkmcnt(0)
	s_barrier
	s_setprio 1
	s_waitcnt lgkmcnt(0)
	v_mfma_f32_16x16x32_bf16 v[126:129], v[140:143], v[174:177], 0
	v_mfma_f32_16x16x32_bf16 v[122:125], v[150:153], v[174:177], 0
	v_mfma_f32_16x16x32_bf16 v[110:113], v[140:143], v[182:185], 0
	v_mfma_f32_16x16x32_bf16 v[106:109], v[150:153], v[182:185], 0
	v_mfma_f32_16x16x32_bf16 v[94:97], v[140:143], v[190:193], 0
	v_mfma_f32_16x16x32_bf16 v[90:93], v[150:153], v[190:193], 0
	v_mfma_f32_16x16x32_bf16 v[78:81], v[140:143], v[198:201], 0
	v_mfma_f32_16x16x32_bf16 v[74:77], v[150:153], v[198:201], 0
	v_mfma_f32_16x16x32_bf16 v[126:129], v[144:147], v[178:181], v[126:129]
	v_mfma_f32_16x16x32_bf16 v[122:125], v[154:157], v[178:181], v[122:125]
	v_mfma_f32_16x16x32_bf16 v[110:113], v[144:147], v[186:189], v[110:113]
	v_mfma_f32_16x16x32_bf16 v[106:109], v[154:157], v[186:189], v[106:109]
	v_mfma_f32_16x16x32_bf16 v[94:97], v[144:147], v[194:197], v[94:97]
	v_mfma_f32_16x16x32_bf16 v[90:93], v[154:157], v[194:197], v[90:93]
	v_mfma_f32_16x16x32_bf16 v[78:81], v[144:147], v[208:211], v[78:81]
	v_mfma_f32_16x16x32_bf16 v[74:77], v[154:157], v[208:211], v[74:77]
	s_setprio 0
	s_setprio 1
	v_mfma_f32_16x16x32_bf16 v[118:121], v[158:161], v[174:177], 0
	v_mfma_f32_16x16x32_bf16 v[114:117], v[166:169], v[174:177], 0
	v_mfma_f32_16x16x32_bf16 v[102:105], v[158:161], v[182:185], 0
	v_mfma_f32_16x16x32_bf16 v[98:101], v[166:169], v[182:185], 0
	v_mfma_f32_16x16x32_bf16 v[86:89], v[158:161], v[190:193], 0
	v_mfma_f32_16x16x32_bf16 v[82:85], v[166:169], v[190:193], 0
	v_mfma_f32_16x16x32_bf16 v[70:73], v[158:161], v[198:201], 0
	v_mfma_f32_16x16x32_bf16 v[66:69], v[166:169], v[198:201], 0
	v_mfma_f32_16x16x32_bf16 v[118:121], v[162:165], v[178:181], v[118:121]
	v_mfma_f32_16x16x32_bf16 v[114:117], v[170:173], v[178:181], v[114:117]
	v_mfma_f32_16x16x32_bf16 v[102:105], v[162:165], v[186:189], v[102:105]
	v_mfma_f32_16x16x32_bf16 v[98:101], v[170:173], v[186:189], v[98:101]
	v_mfma_f32_16x16x32_bf16 v[86:89], v[162:165], v[194:197], v[86:89]
	v_mfma_f32_16x16x32_bf16 v[82:85], v[170:173], v[194:197], v[82:85]
	v_mfma_f32_16x16x32_bf16 v[70:73], v[162:165], v[208:211], v[70:73]
	v_mfma_f32_16x16x32_bf16 v[66:69], v[170:173], v[208:211], v[66:69]
	s_setprio 0
	s_barrier
	s_add_i32 s10, s38, s40
	v_lshl_add_u64 v[212:213], s[12:13], 0, v[0:1]
	s_mov_b32 m0, s10
	ds_read_b128 v[174:177], v149 offset:16384
	ds_read_b128 v[178:181], v149 offset:17408
	ds_read_b128 v[182:185], v149 offset:18432
	ds_read_b128 v[186:189], v149 offset:19456
	ds_read_b128 v[190:193], v149 offset:20480
	ds_read_b128 v[194:197], v149 offset:21504
	ds_read_b128 v[198:201], v149 offset:22528
	ds_read_b128 v[208:211], v149 offset:23552
	global_load_lds_dwordx4 v[212:213], off
	s_add_i32 m0, s10, 0x2000
	s_add_u32 s10, s12, 0x18000
	v_lshl_add_u64 v[214:215], s[12:13], 0, v[130:131]
	s_addc_u32 s11, s13, 0
	s_add_i32 s38, s39, s40
	global_load_lds_dwordx4 v[214:215], off
	v_lshl_add_u64 v[216:217], s[10:11], 0, v[0:1]
	s_mov_b32 m0, s38
	v_lshl_add_u64 v[218:219], s[14:15], 0, v[132:133]
	global_load_lds_dwordx4 v[216:217], off
	v_lshl_add_u64 v[216:217], s[10:11], 0, v[130:131]
	s_add_i32 m0, s38, 0x2000
	s_nop 0
	global_load_lds_dwordx4 v[216:217], off
	v_lshl_add_u64 v[216:217], s[14:15], 0, v[134:135]
	s_mov_b32 m0, s45
	s_nop 0
	global_load_lds_dwordx4 v[216:217], off
	s_mov_b32 m0, s46
	s_nop 0
	global_load_lds_dwordx4 v[218:219], off
	s_waitcnt vmcnt(8)
	s_waitcnt lgkmcnt(0)
	s_barrier
; #define PG8_STAGE(bufoff, gbase, voff) do { _Pragma("unroll") for (int _i = 0; _i < 2; ++_i) \
;         __builtin_amdgcn_global_load_lds((const unsigned*)((const char*)(gbase) + (voff)[_i]), (LAS unsigned*)(lds + (bufoff) + ldsw + _i * 8192), 16, 0, 0); } while (0)
; #define PG8_LDA(dst, b, h) do { _Pragma("unroll") for (int m = 0; m < 4; ++m) _Pragma("unroll") for (int k = 0; k < 2; ++k) dst[m][k] = *(const LAS bf16x8*)(lds + PG8_SA(b, h) + aoff + m * 2048 + k * 1024); } while (0)
; #define PG8_LDB(dst, b, h) do { _Pragma("unroll") for (int n = 0; n < 2; ++n) _Pragma("unroll") for (int k = 0; k < 2; ++k) dst[n][k] = *(const LAS bf16x8*)(lds + PG8_SB(b, h) + boff + n * 2048 + k * 1024); } while (0)
; #define PG8_MMA(ai, bj, At, Bt) do { __builtin_amdgcn_s_setprio(1); _Pragma("unroll") for (int m = 0; m < 4; ++m) _Pragma("unroll") for (int n = 0; n < 2; ++n) _Pragma("unroll") for (int k = 0; k < 2; ++k) \
;         acc[ai][bj][m][n] = __builtin_amdgcn_mfma_f32_16x16x32_bf16(Bt[n][k], At[m][k], acc[ai][bj][m][n], 0, 0, 0); __builtin_amdgcn_s_setprio(0); } while (0)
; #define PG8_WAIT_V(n) asm volatile("s_waitcnt vmcnt(" #n ")" ::: "memory")
; #define PG8_WAIT_L(n) asm volatile("s_waitcnt lgkmcnt(" #n ")" ::: "memory")
; #define PG8_BAR __builtin_amdgcn_s_barrier()
; #define PG8_SCHED __builtin_amdgcn_sched_barrier(0)
; template <class Epi, bool HALFM = false>
; DI void gemm_phase(LAS unsigned char* lds, const Gemm g, const StaticOrder& S, const Epi& E) {
;     ...
;             PG8_WAIT_V(8); PG8_WAIT_L(0); PG8_BAR; if constexpr (!HALFM) { PG8_MMA(1, 0, At, B0); PG8_MMA(1, 1, At, B1); } PG8_BAR; PG8_SCHED;
;             PG8_LDB(B0, 1, 0); PG8_LDB(B1, 1, 1); PG8_SCHED; PG8_LDA(At, 1, 0); PG8_STAGE(PG8_SA(0, 1), a2 + hstepA, voffA);
;             PG8_WAIT_V(8); PG8_WAIT_L(0); PG8_BAR; PG8_MMA(0, 0, At, B0); PG8_MMA(0, 1, At, B1); PG8_BAR; PG8_SCHED;
	s_setprio 1
	s_waitcnt lgkmcnt(0)
	v_mfma_f32_16x16x32_bf16 v[62:65], v[140:143], v[174:177], 0
	v_mfma_f32_16x16x32_bf16 v[58:61], v[150:153], v[174:177], 0
	v_mfma_f32_16x16x32_bf16 v[46:49], v[140:143], v[182:185], 0
	v_mfma_f32_16x16x32_bf16 v[42:45], v[150:153], v[182:185], 0
	v_mfma_f32_16x16x32_bf16 v[30:33], v[140:143], v[190:193], 0
	v_mfma_f32_16x16x32_bf16 v[26:29], v[150:153], v[190:193], 0
	v_mfma_f32_16x16x32_bf16 v[14:17], v[140:143], v[198:201], 0
	v_mfma_f32_16x16x32_bf16 v[10:13], v[150:153], v[198:201], 0
	v_mfma_f32_16x16x32_bf16 v[62:65], v[144:147], v[178:181], v[62:65]
	v_mfma_f32_16x16x32_bf16 v[58:61], v[154:157], v[178:181], v[58:61]
	v_mfma_f32_16x16x32_bf16 v[46:49], v[144:147], v[186:189], v[46:49]
	v_mfma_f32_16x16x32_bf16 v[42:45], v[154:157], v[186:189], v[42:45]
	v_mfma_f32_16x16x32_bf16 v[30:33], v[144:147], v[194:197], v[30:33]
	v_mfma_f32_16x16x32_bf16 v[26:29], v[154:157], v[194:197], v[26:29]
	v_mfma_f32_16x16x32_bf16 v[14:17], v[144:147], v[208:211], v[14:17]
	v_mfma_f32_16x16x32_bf16 v[10:13], v[154:157], v[208:211], v[10:13]
	s_setprio 0
	s_setprio 1
	v_mfma_f32_16x16x32_bf16 v[54:57], v[158:161], v[174:177], 0
	v_mfma_f32_16x16x32_bf16 v[50:53], v[166:169], v[174:177], 0
	v_mfma_f32_16x16x32_bf16 v[38:41], v[158:161], v[182:185], 0
	v_mfma_f32_16x16x32_bf16 v[34:37], v[166:169], v[182:185], 0
	v_mfma_f32_16x16x32_bf16 v[22:25], v[158:161], v[190:193], 0
	v_mfma_f32_16x16x32_bf16 v[18:21], v[166:169], v[190:193], 0
	v_mfma_f32_16x16x32_bf16 v[6:9], v[158:161], v[198:201], 0
	v_mfma_f32_16x16x32_bf16 v[2:5], v[166:169], v[198:201], 0
	v_mfma_f32_16x16x32_bf16 v[54:57], v[162:165], v[178:181], v[54:57]
	v_mfma_f32_16x16x32_bf16 v[50:53], v[170:173], v[178:181], v[50:53]
	v_mfma_f32_16x16x32_bf16 v[38:41], v[162:165], v[186:189], v[38:41]
	v_mfma_f32_16x16x32_bf16 v[34:37], v[170:173], v[186:189], v[34:37]
	v_mfma_f32_16x16x32_bf16 v[22:25], v[162:165], v[194:197], v[22:25]
	v_mfma_f32_16x16x32_bf16 v[18:21], v[170:173], v[194:197], v[18:21]
	v_mfma_f32_16x16x32_bf16 v[6:9], v[162:165], v[208:211], v[6:9]
	v_mfma_f32_16x16x32_bf16 v[2:5], v[170:173], v[208:211], v[2:5]
	s_setprio 0
	s_barrier
	s_add_i32 s38, s92, 0x100
	s_add_i32 s39, s93, 0x100
	v_add_u32_e32 v154, s38, v148
	v_add_u32_e32 v170, s39, v148
	ds_read_b128 v[140:143], v154
	ds_read_b128 v[144:147], v154 offset:1024
	ds_read_b128 v[150:153], v154 offset:2048
	ds_read_b128 v[154:157], v154 offset:3072
	ds_read_b128 v[158:161], v170
	ds_read_b128 v[162:165], v170 offset:1024
	ds_read_b128 v[166:169], v170 offset:2048
	ds_read_b128 v[170:173], v170 offset:3072
	s_add_u32 s10, s14, 0x270000
	s_addc_u32 s11, s15, 0
	s_mov_b32 m0, s47
	v_lshl_add_u64 v[220:221], s[10:11], 0, v[134:135]
	ds_read_b128 v[174:177], v149 offset:32768
	ds_read_b128 v[178:181], v149 offset:33792
	ds_read_b128 v[182:185], v149 offset:34816
	ds_read_b128 v[186:189], v149 offset:35840
	ds_read_b128 v[190:193], v149 offset:36864
	ds_read_b128 v[194:197], v149 offset:37888
	ds_read_b128 v[198:201], v149 offset:38912
	ds_read_b128 v[208:211], v149 offset:39936
	global_load_lds_dwordx4 v[220:221], off
	v_lshl_add_u64 v[220:221], s[10:11], 0, v[132:133]
	s_mov_b32 m0, s48
	s_nop 0
	global_load_lds_dwordx4 v[220:221], off
	s_waitcnt vmcnt(8)
	s_waitcnt lgkmcnt(0)
	s_barrier
	s_setprio 1
	s_waitcnt lgkmcnt(0)
	v_mfma_f32_16x16x32_bf16 v[126:129], v[140:143], v[174:177], v[126:129]
	v_mfma_f32_16x16x32_bf16 v[122:125], v[150:153], v[174:177], v[122:125]
	v_mfma_f32_16x16x32_bf16 v[110:113], v[140:143], v[182:185], v[110:113]
	v_mfma_f32_16x16x32_bf16 v[106:109], v[150:153], v[182:185], v[106:109]
	v_mfma_f32_16x16x32_bf16 v[94:97], v[140:143], v[190:193], v[94:97]
	v_mfma_f32_16x16x32_bf16 v[90:93], v[150:153], v[190:193], v[90:93]
	v_mfma_f32_16x16x32_bf16 v[78:81], v[140:143], v[198:201], v[78:81]
	v_mfma_f32_16x16x32_bf16 v[74:77], v[150:153], v[198:201], v[74:77]
	v_mfma_f32_16x16x32_bf16 v[126:129], v[144:147], v[178:181], v[126:129]
	v_mfma_f32_16x16x32_bf16 v[122:125], v[154:157], v[178:181], v[122:125]
	v_mfma_f32_16x16x32_bf16 v[110:113], v[144:147], v[186:189], v[110:113]
	v_mfma_f32_16x16x32_bf16 v[106:109], v[154:157], v[186:189], v[106:109]
	v_mfma_f32_16x16x32_bf16 v[94:97], v[144:147], v[194:197], v[94:97]
	v_mfma_f32_16x16x32_bf16 v[90:93], v[154:157], v[194:197], v[90:93]
	v_mfma_f32_16x16x32_bf16 v[78:81], v[144:147], v[208:211], v[78:81]
	v_mfma_f32_16x16x32_bf16 v[74:77], v[154:157], v[208:211], v[74:77]
	s_setprio 0
	s_setprio 1
	v_mfma_f32_16x16x32_bf16 v[118:121], v[158:161], v[174:177], v[118:121]
	v_mfma_f32_16x16x32_bf16 v[114:117], v[166:169], v[174:177], v[114:117]
	v_mfma_f32_16x16x32_bf16 v[102:105], v[158:161], v[182:185], v[102:105]
	v_mfma_f32_16x16x32_bf16 v[98:101], v[166:169], v[182:185], v[98:101]
	v_mfma_f32_16x16x32_bf16 v[86:89], v[158:161], v[190:193], v[86:89]
	v_mfma_f32_16x16x32_bf16 v[82:85], v[166:169], v[190:193], v[82:85]
	v_mfma_f32_16x16x32_bf16 v[70:73], v[158:161], v[198:201], v[70:73]
	v_mfma_f32_16x16x32_bf16 v[66:69], v[166:169], v[198:201], v[66:69]
	v_mfma_f32_16x16x32_bf16 v[118:121], v[162:165], v[178:181], v[118:121]
	v_mfma_f32_16x16x32_bf16 v[114:117], v[170:173], v[178:181], v[114:117]
	v_mfma_f32_16x16x32_bf16 v[102:105], v[162:165], v[186:189], v[102:105]
	v_mfma_f32_16x16x32_bf16 v[98:101], v[170:173], v[186:189], v[98:101]
	v_mfma_f32_16x16x32_bf16 v[86:89], v[162:165], v[194:197], v[86:89]
	v_mfma_f32_16x16x32_bf16 v[82:85], v[170:173], v[194:197], v[82:85]
	v_mfma_f32_16x16x32_bf16 v[70:73], v[162:165], v[208:211], v[70:73]
	v_mfma_f32_16x16x32_bf16 v[66:69], v[170:173], v[208:211], v[66:69]
	s_setprio 0
	s_barrier
; #define PG8_STAGE(bufoff, gbase, voff) do { _Pragma("unroll") for (int _i = 0; _i < 2; ++_i) \
;         __builtin_amdgcn_global_load_lds((const unsigned*)((const char*)(gbase) + (voff)[_i]), (LAS unsigned*)(lds + (bufoff) + ldsw + _i * 8192), 16, 0, 0); } while (0)
; #define PG8_LDA(dst, b, h) do { _Pragma("unroll") for (int m = 0; m < 4; ++m) _Pragma("unroll") for (int k = 0; k < 2; ++k) dst[m][k] = *(const LAS bf16x8*)(lds + PG8_SA(b, h) + aoff + m * 2048 + k * 1024); } while (0)
; #define PG8_MMA(ai, bj, At, Bt) do { __builtin_amdgcn_s_setprio(1); _Pragma("unroll") for (int m = 0; m < 4; ++m) _Pragma("unroll") for (int n = 0; n < 2; ++n) _Pragma("unroll") for (int k = 0; k < 2; ++k) \
;         acc[ai][bj][m][n] = __builtin_amdgcn_mfma_f32_16x16x32_bf16(Bt[n][k], At[m][k], acc[ai][bj][m][n], 0, 0, 0); __builtin_amdgcn_s_setprio(0); } while (0)
; #define PG8_WAIT_V(n) asm volatile("s_waitcnt vmcnt(" #n ")" ::: "memory")
; #define PG8_WAIT_L(n) asm volatile("s_waitcnt lgkmcnt(" #n ")" ::: "memory")
; #define PG8_BAR __builtin_amdgcn_s_barrier()
; #define PG8_SCHED __builtin_amdgcn_sched_barrier(0)
; template <class Epi, bool HALFM = false>
; DI void gemm_phase(LAS unsigned char* lds, const Gemm g, const StaticOrder& S, const Epi& E) {
;     ...
;             if constexpr (!HALFM) PG8_LDA(At, 1, 1);
;             PG8_STAGE(PG8_SB(1, 0), b3, voffB); PG8_STAGE(PG8_SB(1, 1), b3 + hstepB, voffB); PG8_STAGE(PG8_SA(1, 0), a3, voffA);
;             PG8_WAIT_V(8); PG8_WAIT_L(0); PG8_BAR; if constexpr (!HALFM) { PG8_MMA(1, 0, At, B0); PG8_MMA(1, 1, At, B1); } PG8_BAR; PG8_SCHED;
	s_add_i32 s10, s38, s40
	v_lshl_add_u64 v[212:213], v[212:213], 0, s[2:3]
	s_mov_b32 m0, s10
	ds_read_b128 v[174:177], v149 offset:49152
	ds_read_b128 v[178:181], v149 offset:50176
	ds_read_b128 v[182:185], v149 offset:51200
	ds_read_b128 v[186:189], v149 offset:52224
	ds_read_b128 v[190:193], v149 offset:53248
	ds_read_b128 v[194:197], v149 offset:54272
	ds_read_b128 v[198:201], v149 offset:55296
	ds_read_b128 v[208:211], v149 offset:56320
	global_load_lds_dwordx4 v[212:213], off
	s_add_i32 m0, s10, 0x2000
	s_add_u32 s10, s12, 0x18080
	v_lshl_add_u64 v[212:213], v[214:215], 0, s[2:3]
	s_addc_u32 s11, s13, 0
	s_add_i32 s12, s39, s40
	global_load_lds_dwordx4 v[212:213], off
	v_lshl_add_u64 v[212:213], s[10:11], 0, v[0:1]
	s_mov_b32 m0, s12
	s_nop 0
	global_load_lds_dwordx4 v[212:213], off
	v_lshl_add_u64 v[212:213], s[10:11], 0, v[130:131]
	s_add_i32 m0, s12, 0x2000
	s_nop 0
	global_load_lds_dwordx4 v[212:213], off
	v_lshl_add_u64 v[212:213], v[216:217], 0, s[2:3]
	s_mov_b32 m0, s51
	s_nop 0
	global_load_lds_dwordx4 v[212:213], off
	v_lshl_add_u64 v[212:213], v[218:219], 0, s[2:3]
	s_mov_b32 m0, s52
	s_nop 0
	global_load_lds_dwordx4 v[212:213], off
	s_waitcnt vmcnt(8)
	s_waitcnt lgkmcnt(0)
	s_barrier
	s_setprio 1
	s_waitcnt lgkmcnt(0)
	v_mfma_f32_16x16x32_bf16 v[62:65], v[140:143], v[174:177], v[62:65]
	v_mfma_f32_16x16x32_bf16 v[58:61], v[150:153], v[174:177], v[58:61]
	v_mfma_f32_16x16x32_bf16 v[46:49], v[140:143], v[182:185], v[46:49]
	v_mfma_f32_16x16x32_bf16 v[42:45], v[150:153], v[182:185], v[42:45]
	v_mfma_f32_16x16x32_bf16 v[30:33], v[140:143], v[190:193], v[30:33]
	v_mfma_f32_16x16x32_bf16 v[26:29], v[150:153], v[190:193], v[26:29]
	v_mfma_f32_16x16x32_bf16 v[14:17], v[140:143], v[198:201], v[14:17]
	v_mfma_f32_16x16x32_bf16 v[10:13], v[150:153], v[198:201], v[10:13]
	v_mfma_f32_16x16x32_bf16 v[62:65], v[144:147], v[178:181], v[62:65]
	v_mfma_f32_16x16x32_bf16 v[58:61], v[154:157], v[178:181], v[58:61]
	v_mfma_f32_16x16x32_bf16 v[46:49], v[144:147], v[186:189], v[46:49]
	v_mfma_f32_16x16x32_bf16 v[42:45], v[154:157], v[186:189], v[42:45]
	v_mfma_f32_16x16x32_bf16 v[30:33], v[144:147], v[194:197], v[30:33]
	v_mfma_f32_16x16x32_bf16 v[26:29], v[154:157], v[194:197], v[26:29]
	v_mfma_f32_16x16x32_bf16 v[14:17], v[144:147], v[208:211], v[14:17]
	v_mfma_f32_16x16x32_bf16 v[10:13], v[154:157], v[208:211], v[10:13]
	s_setprio 0
	s_setprio 1
	v_mfma_f32_16x16x32_bf16 v[54:57], v[158:161], v[174:177], v[54:57]
	v_mfma_f32_16x16x32_bf16 v[50:53], v[166:169], v[174:177], v[50:53]
	v_mfma_f32_16x16x32_bf16 v[38:41], v[158:161], v[182:185], v[38:41]
	v_mfma_f32_16x16x32_bf16 v[34:37], v[166:169], v[182:185], v[34:37]
	v_mfma_f32_16x16x32_bf16 v[22:25], v[158:161], v[190:193], v[22:25]
	v_mfma_f32_16x16x32_bf16 v[18:21], v[166:169], v[190:193], v[18:21]
	v_mfma_f32_16x16x32_bf16 v[6:9], v[158:161], v[198:201], v[6:9]
	v_mfma_f32_16x16x32_bf16 v[2:5], v[166:169], v[198:201], v[2:5]
	v_mfma_f32_16x16x32_bf16 v[54:57], v[162:165], v[178:181], v[54:57]
	v_mfma_f32_16x16x32_bf16 v[50:53], v[170:173], v[178:181], v[50:53]
	v_mfma_f32_16x16x32_bf16 v[38:41], v[162:165], v[186:189], v[38:41]
	v_mfma_f32_16x16x32_bf16 v[34:37], v[170:173], v[186:189], v[34:37]
	v_mfma_f32_16x16x32_bf16 v[22:25], v[162:165], v[194:197], v[22:25]
	v_mfma_f32_16x16x32_bf16 v[18:21], v[170:173], v[194:197], v[18:21]
	v_mfma_f32_16x16x32_bf16 v[6:9], v[162:165], v[208:211], v[6:9]
	v_mfma_f32_16x16x32_bf16 v[2:5], v[170:173], v[208:211], v[2:5]
	s_setprio 0
	s_barrier
	s_add_i32 s33, s33, 2
	s_add_u32 s4, s4, 0x100
	s_addc_u32 s5, s5, 0
	s_cmp_gt_u32 s33, 3
	s_mov_b64 s[10:11], s[6:7]

; #define PG8_STAGE(bufoff, gbase, voff) do { _Pragma("unroll") for (int _i = 0; _i < 2; ++_i) \
;         __builtin_amdgcn_global_load_lds((const unsigned*)((const char*)(gbase) + (voff)[_i]), (LAS unsigned*)(lds + (bufoff) + ldsw + _i * 8192), 16, 0, 0); } while (0)
; #define PG8_LDA(dst, b, h) do { _Pragma("unroll") for (int m = 0; m < 4; ++m) _Pragma("unroll") for (int k = 0; k < 2; ++k) dst[m][k] = *(const LAS bf16x8*)(lds + PG8_SA(b, h) + aoff + m * 2048 + k * 1024); } while (0)
; #define PG8_LDB(dst, b, h) do { _Pragma("unroll") for (int n = 0; n < 2; ++n) _Pragma("unroll") for (int k = 0; k < 2; ++k) dst[n][k] = *(const LAS bf16x8*)(lds + PG8_SB(b, h) + boff + n * 2048 + k * 1024); } while (0)
; #define PG8_MMA(ai, bj, At, Bt) do { __builtin_amdgcn_s_setprio(1); _Pragma("unroll") for (int m = 0; m < 4; ++m) _Pragma("unroll") for (int n = 0; n < 2; ++n) _Pragma("unroll") for (int k = 0; k < 2; ++k) \
;         acc[ai][bj][m][n] = __builtin_amdgcn_mfma_f32_16x16x32_bf16(Bt[n][k], At[m][k], acc[ai][bj][m][n], 0, 0, 0); __builtin_amdgcn_s_setprio(0); } while (0)
; template <class Epi, bool HALFM = false>
; DI void gemm_phase(LAS unsigned char* lds, const Gemm g, const StaticOrder& S, const Epi& E) {
;     ...
; #pragma unroll
;     for (int a = 0; a < 2; ++a)
; #pragma unroll
;         for (int b = 0; b < 2; ++b)
; #pragma unroll
;             for (int m = 0; m < 4; ++m)
; #pragma unroll
;                 for (int n = 0; n < 2; ++n) acc[a][b][m][n] = (f32x4){0.f, 0.f, 0.f, 0.f};
;     ...
;             const bool last = (t == nt - 2);
;             const char* a1 = cA + (size_t)(t + 1) * kstep;
;             const char* a2 = last ? nA : cA + (size_t)(t + 2) * kstep; const char* b2 = last ? nB : cB + (size_t)(t + 2) * kstep;
;             const char* a3 = a2 + kstep; const char* b3 = b2 + kstep;
;             PG8_LDB(B0, 0, 0); PG8_LDB(B1, 0, 1); PG8_SCHED; PG8_LDA(At, 0, 0); PG8_STAGE(PG8_SA(1, 1), a1 + hstepA, voffA);
;             PG8_WAIT_V(8); PG8_WAIT_L(0); PG8_BAR; PG8_MMA(0, 0, At, B0); PG8_MMA(0, 1, At, B1); PG8_BAR; PG8_SCHED;
;             if constexpr (!HALFM) PG8_LDA(At, 0, 1);
;             PG8_STAGE(PG8_SB(0, 0), b2, voffB); PG8_STAGE(PG8_SB(0, 1), b2 + hstepB, voffB); PG8_STAGE(PG8_SA(0, 0), a2, voffA);
;             PG8_WAIT_V(8); PG8_WAIT_L(0); PG8_BAR; if constexpr (!HALFM) { PG8_MMA(1, 0, At, B0); PG8_MMA(1, 1, At, B1); } PG8_BAR; PG8_SCHED;
.LBB0_432:
	s_ashr_i32 s43, s42, 31
	s_lshl_b64 s[4:5], s[42:43], 19
	s_add_u32 s44, s51, s4
	s_addc_u32 s45, s52, s5
	s_and_b64 s[4:5], s[8:9], exec
	s_cselect_b32 s4, s45, s7
	s_cselect_b32 s5, s44, s6
	s_ashr_i32 s41, s40, 31
	s_lshl_b64 s[12:13], s[40:41], 19
	s_add_u32 s46, s53, s12
	s_addc_u32 s47, s54, s13
	s_and_b64 s[12:13], s[8:9], exec
	s_cselect_b32 s14, s47, s11
	s_cselect_b32 s15, s46, s10
	s_add_u32 s6, s6, 0x40080
	s_addc_u32 s7, s7, 0
	s_add_u32 s16, s10, 0x100
	s_addc_u32 s17, s11, 0
	s_mov_b32 s33, -2
	s_waitcnt lgkmcnt(0)
	s_add_u32 s10, s6, 0xfffc0080
	s_addc_u32 s11, s7, -1
	s_add_i32 s41, s90, 0x100
	s_cmp_eq_u32 s33, 12
	s_cselect_b32 s13, s4, s11
	s_cselect_b32 s12, s5, s10
	s_cselect_b32 s11, s14, s17
	s_cselect_b32 s10, s15, s16
	s_add_i32 s43, s91, 0x100
	v_add_u32_e32 v154, s41, v148
	v_add_u32_e32 v170, s43, v148
	ds_read_b128 v[140:143], v154
	ds_read_b128 v[144:147], v154 offset:1024
	ds_read_b128 v[150:153], v154 offset:2048
	ds_read_b128 v[154:157], v154 offset:3072
	ds_read_b128 v[158:161], v170
	ds_read_b128 v[162:165], v170 offset:1024
	ds_read_b128 v[166:169], v170 offset:2048
	ds_read_b128 v[170:173], v170 offset:3072
	v_lshl_add_u64 v[212:213], s[6:7], 0, v[136:137]
	s_add_i32 m0, s55, 0xc000
	ds_read_b128 v[174:177], v149
	ds_read_b128 v[178:181], v149 offset:1024
	ds_read_b128 v[182:185], v149 offset:2048
	ds_read_b128 v[186:189], v149 offset:3072
	ds_read_b128 v[190:193], v149 offset:4096
	ds_read_b128 v[194:197], v149 offset:5120
	ds_read_b128 v[198:201], v149 offset:6144
	ds_read_b128 v[208:211], v149 offset:7168
	global_load_lds_dwordx4 v[212:213], off
	v_lshl_add_u64 v[212:213], s[6:7], 0, v[138:139]
	s_add_i32 m0, s55, 0xe000
	s_nop 0
	global_load_lds_dwordx4 v[212:213], off
	s_waitcnt vmcnt(8)
	s_waitcnt lgkmcnt(0)
	s_barrier
	s_setprio 1
	s_waitcnt lgkmcnt(0)
	v_mfma_f32_16x16x32_bf16 v[126:129], v[140:143], v[174:177], 0
	v_mfma_f32_16x16x32_bf16 v[122:125], v[150:153], v[174:177], 0
	v_mfma_f32_16x16x32_bf16 v[110:113], v[140:143], v[182:185], 0
	v_mfma_f32_16x16x32_bf16 v[106:109], v[150:153], v[182:185], 0
	v_mfma_f32_16x16x32_bf16 v[94:97], v[140:143], v[190:193], 0
	v_mfma_f32_16x16x32_bf16 v[90:93], v[150:153], v[190:193], 0
	v_mfma_f32_16x16x32_bf16 v[78:81], v[140:143], v[198:201], 0
	v_mfma_f32_16x16x32_bf16 v[74:77], v[150:153], v[198:201], 0
	v_mfma_f32_16x16x32_bf16 v[126:129], v[144:147], v[178:181], v[126:129]
	v_mfma_f32_16x16x32_bf16 v[122:125], v[154:157], v[178:181], v[122:125]
	v_mfma_f32_16x16x32_bf16 v[110:113], v[144:147], v[186:189], v[110:113]
	v_mfma_f32_16x16x32_bf16 v[106:109], v[154:157], v[186:189], v[106:109]
	v_mfma_f32_16x16x32_bf16 v[94:97], v[144:147], v[194:197], v[94:97]
	v_mfma_f32_16x16x32_bf16 v[90:93], v[154:157], v[194:197], v[90:93]
	v_mfma_f32_16x16x32_bf16 v[78:81], v[144:147], v[208:211], v[78:81]
	v_mfma_f32_16x16x32_bf16 v[74:77], v[154:157], v[208:211], v[74:77]
	s_setprio 0
	s_setprio 1
	v_mfma_f32_16x16x32_bf16 v[118:121], v[158:161], v[174:177], 0
	v_mfma_f32_16x16x32_bf16 v[114:117], v[166:169], v[174:177], 0
	v_mfma_f32_16x16x32_bf16 v[102:105], v[158:161], v[182:185], 0
	v_mfma_f32_16x16x32_bf16 v[98:101], v[166:169], v[182:185], 0
	v_mfma_f32_16x16x32_bf16 v[86:89], v[158:161], v[190:193], 0
	v_mfma_f32_16x16x32_bf16 v[82:85], v[166:169], v[190:193], 0
	v_mfma_f32_16x16x32_bf16 v[70:73], v[158:161], v[198:201], 0
	v_mfma_f32_16x16x32_bf16 v[66:69], v[166:169], v[198:201], 0
	v_mfma_f32_16x16x32_bf16 v[118:121], v[162:165], v[178:181], v[118:121]
	v_mfma_f32_16x16x32_bf16 v[114:117], v[170:173], v[178:181], v[114:117]
	v_mfma_f32_16x16x32_bf16 v[102:105], v[162:165], v[186:189], v[102:105]
	v_mfma_f32_16x16x32_bf16 v[98:101], v[170:173], v[186:189], v[98:101]
	v_mfma_f32_16x16x32_bf16 v[86:89], v[162:165], v[194:197], v[86:89]
	v_mfma_f32_16x16x32_bf16 v[82:85], v[170:173], v[194:197], v[82:85]
	v_mfma_f32_16x16x32_bf16 v[70:73], v[162:165], v[208:211], v[70:73]
	v_mfma_f32_16x16x32_bf16 v[66:69], v[170:173], v[208:211], v[66:69]
	s_setprio 0
	s_barrier
	s_add_i32 s41, s41, s50
	v_lshl_add_u64 v[212:213], s[10:11], 0, v[0:1]
	s_mov_b32 m0, s41
	ds_read_b128 v[174:177], v149 offset:16384
	ds_read_b128 v[178:181], v149 offset:17408
	ds_read_b128 v[182:185], v149 offset:18432
	ds_read_b128 v[186:189], v149 offset:19456
	ds_read_b128 v[190:193], v149 offset:20480
	ds_read_b128 v[194:197], v149 offset:21504
	ds_read_b128 v[198:201], v149 offset:22528
	ds_read_b128 v[208:211], v149 offset:23552
	global_load_lds_dwordx4 v[212:213], off
	s_add_i32 m0, s41, 0x2000
	s_add_u32 s48, s10, 0x40000
	v_lshl_add_u64 v[214:215], s[10:11], 0, v[130:131]
	s_addc_u32 s49, s11, 0
	s_add_i32 s41, s43, s50
	global_load_lds_dwordx4 v[214:215], off
	v_lshl_add_u64 v[216:217], s[48:49], 0, v[0:1]
	s_mov_b32 m0, s41
	v_lshl_add_u64 v[218:219], s[12:13], 0, v[132:133]
	global_load_lds_dwordx4 v[216:217], off
	v_lshl_add_u64 v[216:217], s[48:49], 0, v[130:131]
	s_add_i32 m0, s41, 0x2000
	s_nop 0
	global_load_lds_dwordx4 v[216:217], off
	v_lshl_add_u64 v[216:217], s[12:13], 0, v[134:135]
	s_mov_b32 m0, s55
	s_nop 0
	global_load_lds_dwordx4 v[216:217], off
	s_mov_b32 m0, s56
	s_nop 0
	global_load_lds_dwordx4 v[218:219], off
	s_waitcnt vmcnt(8)
	s_waitcnt lgkmcnt(0)
	s_barrier
; #define PG8_STAGE(bufoff, gbase, voff) do { _Pragma("unroll") for (int _i = 0; _i < 2; ++_i) \
;         __builtin_amdgcn_global_load_lds((const unsigned*)((const char*)(gbase) + (voff)[_i]), (LAS unsigned*)(lds + (bufoff) + ldsw + _i * 8192), 16, 0, 0); } while (0)
; #define PG8_LDA(dst, b, h) do { _Pragma("unroll") for (int m = 0; m < 4; ++m) _Pragma("unroll") for (int k = 0; k < 2; ++k) dst[m][k] = *(const LAS bf16x8*)(lds + PG8_SA(b, h) + aoff + m * 2048 + k * 1024); } while (0)
; #define PG8_LDB(dst, b, h) do { _Pragma("unroll") for (int n = 0; n < 2; ++n) _Pragma("unroll") for (int k = 0; k < 2; ++k) dst[n][k] = *(const LAS bf16x8*)(lds + PG8_SB(b, h) + boff + n * 2048 + k * 1024); } while (0)
; #define PG8_MMA(ai, bj, At, Bt) do { __builtin_amdgcn_s_setprio(1); _Pragma("unroll") for (int m = 0; m < 4; ++m) _Pragma("unroll") for (int n = 0; n < 2; ++n) _Pragma("unroll") for (int k = 0; k < 2; ++k) \
;         acc[ai][bj][m][n] = __builtin_amdgcn_mfma_f32_16x16x32_bf16(Bt[n][k], At[m][k], acc[ai][bj][m][n], 0, 0, 0); __builtin_amdgcn_s_setprio(0); } while (0)
; #define PG8_WAIT_V(n) asm volatile("s_waitcnt vmcnt(" #n ")" ::: "memory")
; #define PG8_WAIT_L(n) asm volatile("s_waitcnt lgkmcnt(" #n ")" ::: "memory")
; #define PG8_BAR __builtin_amdgcn_s_barrier()
; #define PG8_SCHED __builtin_amdgcn_sched_barrier(0)
; template <class Epi, bool HALFM = false>
; DI void gemm_phase(LAS unsigned char* lds, const Gemm g, const StaticOrder& S, const Epi& E) {
;     ...
;             PG8_WAIT_V(8); PG8_WAIT_L(0); PG8_BAR; if constexpr (!HALFM) { PG8_MMA(1, 0, At, B0); PG8_MMA(1, 1, At, B1); } PG8_BAR; PG8_SCHED;
;             PG8_LDB(B0, 1, 0); PG8_LDB(B1, 1, 1); PG8_SCHED; PG8_LDA(At, 1, 0); PG8_STAGE(PG8_SA(0, 1), a2 + hstepA, voffA);
;             PG8_WAIT_V(8); PG8_WAIT_L(0); PG8_BAR; PG8_MMA(0, 0, At, B0); PG8_MMA(0, 1, At, B1); PG8_BAR; PG8_SCHED;
	s_setprio 1
	s_waitcnt lgkmcnt(0)
	v_mfma_f32_16x16x32_bf16 v[62:65], v[140:143], v[174:177], 0
	v_mfma_f32_16x16x32_bf16 v[58:61], v[150:153], v[174:177], 0
	v_mfma_f32_16x16x32_bf16 v[46:49], v[140:143], v[182:185], 0
	v_mfma_f32_16x16x32_bf16 v[42:45], v[150:153], v[182:185], 0
	v_mfma_f32_16x16x32_bf16 v[30:33], v[140:143], v[190:193], 0
	v_mfma_f32_16x16x32_bf16 v[26:29], v[150:153], v[190:193], 0
	v_mfma_f32_16x16x32_bf16 v[14:17], v[140:143], v[198:201], 0
	v_mfma_f32_16x16x32_bf16 v[10:13], v[150:153], v[198:201], 0
	v_mfma_f32_16x16x32_bf16 v[62:65], v[144:147], v[178:181], v[62:65]
	v_mfma_f32_16x16x32_bf16 v[58:61], v[154:157], v[178:181], v[58:61]
	v_mfma_f32_16x16x32_bf16 v[46:49], v[144:147], v[186:189], v[46:49]
	v_mfma_f32_16x16x32_bf16 v[42:45], v[154:157], v[186:189], v[42:45]
	v_mfma_f32_16x16x32_bf16 v[30:33], v[144:147], v[194:197], v[30:33]
	v_mfma_f32_16x16x32_bf16 v[26:29], v[154:157], v[194:197], v[26:29]
	v_mfma_f32_16x16x32_bf16 v[14:17], v[144:147], v[208:211], v[14:17]
	v_mfma_f32_16x16x32_bf16 v[10:13], v[154:157], v[208:211], v[10:13]
	s_setprio 0
	s_setprio 1
	v_mfma_f32_16x16x32_bf16 v[54:57], v[158:161], v[174:177], 0
	v_mfma_f32_16x16x32_bf16 v[50:53], v[166:169], v[174:177], 0
	v_mfma_f32_16x16x32_bf16 v[38:41], v[158:161], v[182:185], 0
	v_mfma_f32_16x16x32_bf16 v[34:37], v[166:169], v[182:185], 0
	v_mfma_f32_16x16x32_bf16 v[22:25], v[158:161], v[190:193], 0
	v_mfma_f32_16x16x32_bf16 v[18:21], v[166:169], v[190:193], 0
	v_mfma_f32_16x16x32_bf16 v[6:9], v[158:161], v[198:201], 0
	v_mfma_f32_16x16x32_bf16 v[2:5], v[166:169], v[198:201], 0
	v_mfma_f32_16x16x32_bf16 v[54:57], v[162:165], v[178:181], v[54:57]
	v_mfma_f32_16x16x32_bf16 v[50:53], v[170:173], v[178:181], v[50:53]
	v_mfma_f32_16x16x32_bf16 v[38:41], v[162:165], v[186:189], v[38:41]
	v_mfma_f32_16x16x32_bf16 v[34:37], v[170:173], v[186:189], v[34:37]
	v_mfma_f32_16x16x32_bf16 v[22:25], v[162:165], v[194:197], v[22:25]
	v_mfma_f32_16x16x32_bf16 v[18:21], v[170:173], v[194:197], v[18:21]
	v_mfma_f32_16x16x32_bf16 v[6:9], v[162:165], v[208:211], v[6:9]
	v_mfma_f32_16x16x32_bf16 v[2:5], v[170:173], v[208:211], v[2:5]
	s_setprio 0
	s_barrier
	s_add_i32 s41, s92, 0x100
	s_add_i32 s43, s93, 0x100
	v_add_u32_e32 v154, s41, v148
	v_add_u32_e32 v170, s43, v148
	ds_read_b128 v[140:143], v154
	ds_read_b128 v[144:147], v154 offset:1024
	ds_read_b128 v[150:153], v154 offset:2048
	ds_read_b128 v[154:157], v154 offset:3072
	ds_read_b128 v[158:161], v170
	ds_read_b128 v[162:165], v170 offset:1024
	ds_read_b128 v[166:169], v170 offset:2048
	ds_read_b128 v[170:173], v170 offset:3072
	s_add_u32 s12, s12, 0x40000
	s_addc_u32 s13, s13, 0
	s_mov_b32 m0, s57
	v_lshl_add_u64 v[220:221], s[12:13], 0, v[134:135]
	ds_read_b128 v[174:177], v149 offset:32768
	ds_read_b128 v[178:181], v149 offset:33792
	ds_read_b128 v[182:185], v149 offset:34816
	ds_read_b128 v[186:189], v149 offset:35840
	ds_read_b128 v[190:193], v149 offset:36864
	ds_read_b128 v[194:197], v149 offset:37888
	ds_read_b128 v[198:201], v149 offset:38912
	ds_read_b128 v[208:211], v149 offset:39936
	global_load_lds_dwordx4 v[220:221], off
	v_lshl_add_u64 v[220:221], s[12:13], 0, v[132:133]
	s_mov_b32 m0, s58
	s_nop 0
	global_load_lds_dwordx4 v[220:221], off
	s_waitcnt vmcnt(8)
	s_waitcnt lgkmcnt(0)
	s_barrier
	s_setprio 1
	s_waitcnt lgkmcnt(0)
	v_mfma_f32_16x16x32_bf16 v[126:129], v[140:143], v[174:177], v[126:129]
	v_mfma_f32_16x16x32_bf16 v[122:125], v[150:153], v[174:177], v[122:125]
	v_mfma_f32_16x16x32_bf16 v[110:113], v[140:143], v[182:185], v[110:113]
	v_mfma_f32_16x16x32_bf16 v[106:109], v[150:153], v[182:185], v[106:109]
	v_mfma_f32_16x16x32_bf16 v[94:97], v[140:143], v[190:193], v[94:97]
	v_mfma_f32_16x16x32_bf16 v[90:93], v[150:153], v[190:193], v[90:93]
	v_mfma_f32_16x16x32_bf16 v[78:81], v[140:143], v[198:201], v[78:81]
	v_mfma_f32_16x16x32_bf16 v[74:77], v[150:153], v[198:201], v[74:77]
	v_mfma_f32_16x16x32_bf16 v[126:129], v[144:147], v[178:181], v[126:129]
	v_mfma_f32_16x16x32_bf16 v[122:125], v[154:157], v[178:181], v[122:125]
	v_mfma_f32_16x16x32_bf16 v[110:113], v[144:147], v[186:189], v[110:113]
	v_mfma_f32_16x16x32_bf16 v[106:109], v[154:157], v[186:189], v[106:109]
	v_mfma_f32_16x16x32_bf16 v[94:97], v[144:147], v[194:197], v[94:97]
	v_mfma_f32_16x16x32_bf16 v[90:93], v[154:157], v[194:197], v[90:93]
	v_mfma_f32_16x16x32_bf16 v[78:81], v[144:147], v[208:211], v[78:81]
	v_mfma_f32_16x16x32_bf16 v[74:77], v[154:157], v[208:211], v[74:77]
	s_setprio 0
	s_setprio 1
	v_mfma_f32_16x16x32_bf16 v[118:121], v[158:161], v[174:177], v[118:121]
	v_mfma_f32_16x16x32_bf16 v[114:117], v[166:169], v[174:177], v[114:117]
	v_mfma_f32_16x16x32_bf16 v[102:105], v[158:161], v[182:185], v[102:105]
	v_mfma_f32_16x16x32_bf16 v[98:101], v[166:169], v[182:185], v[98:101]
	v_mfma_f32_16x16x32_bf16 v[86:89], v[158:161], v[190:193], v[86:89]
	v_mfma_f32_16x16x32_bf16 v[82:85], v[166:169], v[190:193], v[82:85]
	v_mfma_f32_16x16x32_bf16 v[70:73], v[158:161], v[198:201], v[70:73]
	v_mfma_f32_16x16x32_bf16 v[66:69], v[166:169], v[198:201], v[66:69]
	v_mfma_f32_16x16x32_bf16 v[118:121], v[162:165], v[178:181], v[118:121]
	v_mfma_f32_16x16x32_bf16 v[114:117], v[170:173], v[178:181], v[114:117]
	v_mfma_f32_16x16x32_bf16 v[102:105], v[162:165], v[186:189], v[102:105]
	v_mfma_f32_16x16x32_bf16 v[98:101], v[170:173], v[186:189], v[98:101]
	v_mfma_f32_16x16x32_bf16 v[86:89], v[162:165], v[194:197], v[86:89]
	v_mfma_f32_16x16x32_bf16 v[82:85], v[170:173], v[194:197], v[82:85]
	v_mfma_f32_16x16x32_bf16 v[70:73], v[162:165], v[208:211], v[70:73]
	v_mfma_f32_16x16x32_bf16 v[66:69], v[170:173], v[208:211], v[66:69]
	s_setprio 0
	s_barrier
; #define PG8_STAGE(bufoff, gbase, voff) do { _Pragma("unroll") for (int _i = 0; _i < 2; ++_i) \
;         __builtin_amdgcn_global_load_lds((const unsigned*)((const char*)(gbase) + (voff)[_i]), (LAS unsigned*)(lds + (bufoff) + ldsw + _i * 8192), 16, 0, 0); } while (0)
; #define PG8_LDA(dst, b, h) do { _Pragma("unroll") for (int m = 0; m < 4; ++m) _Pragma("unroll") for (int k = 0; k < 2; ++k) dst[m][k] = *(const LAS bf16x8*)(lds + PG8_SA(b, h) + aoff + m * 2048 + k * 1024); } while (0)
; #define PG8_MMA(ai, bj, At, Bt) do { __builtin_amdgcn_s_setprio(1); _Pragma("unroll") for (int m = 0; m < 4; ++m) _Pragma("unroll") for (int n = 0; n < 2; ++n) _Pragma("unroll") for (int k = 0; k < 2; ++k) \
;         acc[ai][bj][m][n] = __builtin_amdgcn_mfma_f32_16x16x32_bf16(Bt[n][k], At[m][k], acc[ai][bj][m][n], 0, 0, 0); __builtin_amdgcn_s_setprio(0); } while (0)
; #define PG8_WAIT_V(n) asm volatile("s_waitcnt vmcnt(" #n ")" ::: "memory")
; #define PG8_WAIT_L(n) asm volatile("s_waitcnt lgkmcnt(" #n ")" ::: "memory")
; #define PG8_BAR __builtin_amdgcn_s_barrier()
; #define PG8_SCHED __builtin_amdgcn_sched_barrier(0)
; template <class Epi, bool HALFM = false>
; DI void gemm_phase(LAS unsigned char* lds, const Gemm g, const StaticOrder& S, const Epi& E) {
;     ...
;             if constexpr (!HALFM) PG8_LDA(At, 1, 1);
;             PG8_STAGE(PG8_SB(1, 0), b3, voffB); PG8_STAGE(PG8_SB(1, 1), b3 + hstepB, voffB); PG8_STAGE(PG8_SA(1, 0), a3, voffA);
;             PG8_WAIT_V(8); PG8_WAIT_L(0); PG8_BAR; if constexpr (!HALFM) { PG8_MMA(1, 0, At, B0); PG8_MMA(1, 1, At, B1); } PG8_BAR; PG8_SCHED;
	s_add_i32 s12, s41, s50
	v_lshl_add_u64 v[212:213], v[212:213], 0, s[2:3]
	s_mov_b32 m0, s12
	ds_read_b128 v[174:177], v149 offset:49152
	ds_read_b128 v[178:181], v149 offset:50176
	ds_read_b128 v[182:185], v149 offset:51200
	ds_read_b128 v[186:189], v149 offset:52224
	ds_read_b128 v[190:193], v149 offset:53248
	ds_read_b128 v[194:197], v149 offset:54272
	ds_read_b128 v[198:201], v149 offset:55296
	ds_read_b128 v[208:211], v149 offset:56320
	global_load_lds_dwordx4 v[212:213], off
	s_add_i32 m0, s12, 0x2000
	s_add_u32 s10, s10, 0x40080
	v_lshl_add_u64 v[212:213], v[214:215], 0, s[2:3]
	s_addc_u32 s11, s11, 0
	s_add_i32 s12, s43, s50
	global_load_lds_dwordx4 v[212:213], off
	v_lshl_add_u64 v[212:213], s[10:11], 0, v[0:1]
	s_mov_b32 m0, s12
	s_nop 0
	global_load_lds_dwordx4 v[212:213], off
	v_lshl_add_u64 v[212:213], s[10:11], 0, v[130:131]
	s_add_i32 m0, s12, 0x2000
	s_nop 0
	global_load_lds_dwordx4 v[212:213], off
	v_lshl_add_u64 v[212:213], v[216:217], 0, s[2:3]
	s_mov_b32 m0, s61
	s_nop 0
	global_load_lds_dwordx4 v[212:213], off
	v_lshl_add_u64 v[212:213], v[218:219], 0, s[2:3]
	s_mov_b32 m0, s62
	s_nop 0
	global_load_lds_dwordx4 v[212:213], off
	s_waitcnt vmcnt(8)
	s_waitcnt lgkmcnt(0)
	s_barrier
	s_setprio 1
	s_waitcnt lgkmcnt(0)
	v_mfma_f32_16x16x32_bf16 v[62:65], v[140:143], v[174:177], v[62:65]
	v_mfma_f32_16x16x32_bf16 v[58:61], v[150:153], v[174:177], v[58:61]
	v_mfma_f32_16x16x32_bf16 v[46:49], v[140:143], v[182:185], v[46:49]
	v_mfma_f32_16x16x32_bf16 v[42:45], v[150:153], v[182:185], v[42:45]
	v_mfma_f32_16x16x32_bf16 v[30:33], v[140:143], v[190:193], v[30:33]
	v_mfma_f32_16x16x32_bf16 v[26:29], v[150:153], v[190:193], v[26:29]
	v_mfma_f32_16x16x32_bf16 v[14:17], v[140:143], v[198:201], v[14:17]
	v_mfma_f32_16x16x32_bf16 v[10:13], v[150:153], v[198:201], v[10:13]
	v_mfma_f32_16x16x32_bf16 v[62:65], v[144:147], v[178:181], v[62:65]
	v_mfma_f32_16x16x32_bf16 v[58:61], v[154:157], v[178:181], v[58:61]
	v_mfma_f32_16x16x32_bf16 v[46:49], v[144:147], v[186:189], v[46:49]
	v_mfma_f32_16x16x32_bf16 v[42:45], v[154:157], v[186:189], v[42:45]
	v_mfma_f32_16x16x32_bf16 v[30:33], v[144:147], v[194:197], v[30:33]
	v_mfma_f32_16x16x32_bf16 v[26:29], v[154:157], v[194:197], v[26:29]
	v_mfma_f32_16x16x32_bf16 v[14:17], v[144:147], v[208:211], v[14:17]
	v_mfma_f32_16x16x32_bf16 v[10:13], v[154:157], v[208:211], v[10:13]
	s_setprio 0
	s_setprio 1
	v_mfma_f32_16x16x32_bf16 v[54:57], v[158:161], v[174:177], v[54:57]
	v_mfma_f32_16x16x32_bf16 v[50:53], v[166:169], v[174:177], v[50:53]
	v_mfma_f32_16x16x32_bf16 v[38:41], v[158:161], v[182:185], v[38:41]
	v_mfma_f32_16x16x32_bf16 v[34:37], v[166:169], v[182:185], v[34:37]
	v_mfma_f32_16x16x32_bf16 v[22:25], v[158:161], v[190:193], v[22:25]
	v_mfma_f32_16x16x32_bf16 v[18:21], v[166:169], v[190:193], v[18:21]
	v_mfma_f32_16x16x32_bf16 v[6:9], v[158:161], v[198:201], v[6:9]
	v_mfma_f32_16x16x32_bf16 v[2:5], v[166:169], v[198:201], v[2:5]
	v_mfma_f32_16x16x32_bf16 v[54:57], v[162:165], v[178:181], v[54:57]
	v_mfma_f32_16x16x32_bf16 v[50:53], v[170:173], v[178:181], v[50:53]
	v_mfma_f32_16x16x32_bf16 v[38:41], v[162:165], v[186:189], v[38:41]
	v_mfma_f32_16x16x32_bf16 v[34:37], v[170:173], v[186:189], v[34:37]
	v_mfma_f32_16x16x32_bf16 v[22:25], v[162:165], v[194:197], v[22:25]
	v_mfma_f32_16x16x32_bf16 v[18:21], v[170:173], v[194:197], v[18:21]
	v_mfma_f32_16x16x32_bf16 v[6:9], v[162:165], v[208:211], v[6:9]
	v_mfma_f32_16x16x32_bf16 v[2:5], v[170:173], v[208:211], v[2:5]
	s_setprio 0
	s_barrier
	s_add_i32 s33, s33, 2
	s_add_u32 s6, s6, 0x100
	s_addc_u32 s7, s7, 0
	s_add_u32 s16, s16, 0x100
	s_addc_u32 s17, s17, 0
	s_cmp_gt_u32 s33, 13

; #define PG8_STAGE(bufoff, gbase, voff) do { _Pragma("unroll") for (int _i = 0; _i < 2; ++_i) \
;         __builtin_amdgcn_global_load_lds((const unsigned*)((const char*)(gbase) + (voff)[_i]), (LAS unsigned*)(lds + (bufoff) + ldsw + _i * 8192), 16, 0, 0); } while (0)
; #define PG8_LDA(dst, b, h) do { _Pragma("unroll") for (int m = 0; m < 4; ++m) _Pragma("unroll") for (int k = 0; k < 2; ++k) dst[m][k] = *(const LAS bf16x8*)(lds + PG8_SA(b, h) + aoff + m * 2048 + k * 1024); } while (0)
; #define PG8_LDB(dst, b, h) do { _Pragma("unroll") for (int n = 0; n < 2; ++n) _Pragma("unroll") for (int k = 0; k < 2; ++k) dst[n][k] = *(const LAS bf16x8*)(lds + PG8_SB(b, h) + boff + n * 2048 + k * 1024); } while (0)
; #define PG8_MMA(ai, bj, At, Bt) do { __builtin_amdgcn_s_setprio(1); _Pragma("unroll") for (int m = 0; m < 4; ++m) _Pragma("unroll") for (int n = 0; n < 2; ++n) _Pragma("unroll") for (int k = 0; k < 2; ++k) \
;         acc[ai][bj][m][n] = __builtin_amdgcn_mfma_f32_16x16x32_bf16(Bt[n][k], At[m][k], acc[ai][bj][m][n], 0, 0, 0); __builtin_amdgcn_s_setprio(0); } while (0)
; template <class Epi, bool HALFM = false>
; DI void gemm_phase(LAS unsigned char* lds, const Gemm g, const StaticOrder& S, const Epi& E) {
;     ...
; #pragma unroll
;     for (int a = 0; a < 2; ++a)
; #pragma unroll
;         for (int b = 0; b < 2; ++b)
; #pragma unroll
;             for (int m = 0; m < 4; ++m)
; #pragma unroll
;                 for (int n = 0; n < 2; ++n) acc[a][b][m][n] = (f32x4){0.f, 0.f, 0.f, 0.f};
;     ...
;             const bool last = (t == nt - 2);
;             const char* a1 = cA + (size_t)(t + 1) * kstep;
;             const char* a2 = last ? nA : cA + (size_t)(t + 2) * kstep; const char* b2 = last ? nB : cB + (size_t)(t + 2) * kstep;
;             const char* a3 = a2 + kstep; const char* b3 = b2 + kstep;
;             PG8_LDB(B0, 0, 0); PG8_LDB(B1, 0, 1); PG8_SCHED; PG8_LDA(At, 0, 0); PG8_STAGE(PG8_SA(1, 1), a1 + hstepA, voffA);
;             PG8_WAIT_V(8); PG8_WAIT_L(0); PG8_BAR; PG8_MMA(0, 0, At, B0); PG8_MMA(0, 1, At, B1); PG8_BAR; PG8_SCHED;
;             if constexpr (!HALFM) PG8_LDA(At, 0, 1);
;             PG8_STAGE(PG8_SB(0, 0), b2, voffB); PG8_STAGE(PG8_SB(0, 1), b2 + hstepB, voffB); PG8_STAGE(PG8_SA(0, 0), a2, voffA);
;             PG8_WAIT_V(8); PG8_WAIT_L(0); PG8_BAR; if constexpr (!HALFM) { PG8_MMA(1, 0, At, B0); PG8_MMA(1, 1, At, B1); } PG8_BAR; PG8_SCHED;
.LBB0_567:
	s_add_u32 s6, s38, 0x80
	s_addc_u32 s7, s39, 0
	s_add_u32 s38, s36, 0x100
	s_addc_u32 s39, s37, 0
	s_mov_b32 s36, 0
	s_add_i32 s60, s36, 2
	s_add_u32 s61, s6, 0x80
	s_addc_u32 s37, s7, 0
	s_add_i32 s64, s90, 0x100
	s_cmp_eq_u32 s51, s36
	s_cselect_b32 s37, s31, s37
	s_cselect_b32 s36, s30, s61
	s_cselect_b32 s63, s35, s39
	s_cselect_b32 s62, s34, s38
	s_add_i32 s61, s91, 0x100
	v_add_u32_e32 v154, s64, v144
	v_add_u32_e32 v170, s61, v144
	ds_read_b128 v[140:143], v154
	ds_read_b128 v[146:149], v154 offset:1024
	ds_read_b128 v[150:153], v154 offset:2048
	ds_read_b128 v[154:157], v154 offset:3072
	ds_read_b128 v[158:161], v170
	ds_read_b128 v[162:165], v170 offset:1024
	ds_read_b128 v[166:169], v170 offset:2048
	ds_read_b128 v[170:173], v170 offset:3072
	v_lshl_add_u64 v[212:213], s[6:7], 0, v[136:137]
	s_add_i32 m0, s42, 0xc000
	ds_read_b128 v[174:177], v145
	ds_read_b128 v[178:181], v145 offset:1024
	ds_read_b128 v[182:185], v145 offset:2048
	ds_read_b128 v[186:189], v145 offset:3072
	ds_read_b128 v[190:193], v145 offset:4096
	ds_read_b128 v[194:197], v145 offset:5120
	ds_read_b128 v[198:201], v145 offset:6144
	ds_read_b128 v[208:211], v145 offset:7168
	global_load_lds_dwordx4 v[212:213], off
	v_lshl_add_u64 v[212:213], s[6:7], 0, v[138:139]
	s_add_i32 m0, s42, 0xe000
	s_nop 0
	global_load_lds_dwordx4 v[212:213], off
	s_waitcnt vmcnt(8)
	s_waitcnt lgkmcnt(0)
	s_barrier
	s_setprio 1
	s_waitcnt lgkmcnt(0)
	v_mfma_f32_16x16x32_bf16 v[126:129], v[140:143], v[174:177], 0
	v_mfma_f32_16x16x32_bf16 v[122:125], v[150:153], v[174:177], 0
	v_mfma_f32_16x16x32_bf16 v[114:117], v[140:143], v[182:185], 0
	v_mfma_f32_16x16x32_bf16 v[106:109], v[150:153], v[182:185], 0
	v_mfma_f32_16x16x32_bf16 v[98:101], v[140:143], v[190:193], 0
	v_mfma_f32_16x16x32_bf16 v[90:93], v[150:153], v[190:193], 0
	v_mfma_f32_16x16x32_bf16 v[82:85], v[140:143], v[198:201], 0
	v_mfma_f32_16x16x32_bf16 v[74:77], v[150:153], v[198:201], 0
	v_mfma_f32_16x16x32_bf16 v[126:129], v[146:149], v[178:181], v[126:129]
	v_mfma_f32_16x16x32_bf16 v[122:125], v[154:157], v[178:181], v[122:125]
	v_mfma_f32_16x16x32_bf16 v[114:117], v[146:149], v[186:189], v[114:117]
	v_mfma_f32_16x16x32_bf16 v[106:109], v[154:157], v[186:189], v[106:109]
	v_mfma_f32_16x16x32_bf16 v[98:101], v[146:149], v[194:197], v[98:101]
	v_mfma_f32_16x16x32_bf16 v[90:93], v[154:157], v[194:197], v[90:93]
	v_mfma_f32_16x16x32_bf16 v[82:85], v[146:149], v[208:211], v[82:85]
	v_mfma_f32_16x16x32_bf16 v[74:77], v[154:157], v[208:211], v[74:77]
	s_setprio 0
	s_setprio 1
	v_mfma_f32_16x16x32_bf16 v[118:121], v[158:161], v[174:177], 0
	v_mfma_f32_16x16x32_bf16 v[110:113], v[166:169], v[174:177], 0
	v_mfma_f32_16x16x32_bf16 v[102:105], v[158:161], v[182:185], 0
	v_mfma_f32_16x16x32_bf16 v[94:97], v[166:169], v[182:185], 0
	v_mfma_f32_16x16x32_bf16 v[86:89], v[158:161], v[190:193], 0
	v_mfma_f32_16x16x32_bf16 v[78:81], v[166:169], v[190:193], 0
	v_mfma_f32_16x16x32_bf16 v[70:73], v[158:161], v[198:201], 0
	v_mfma_f32_16x16x32_bf16 v[66:69], v[166:169], v[198:201], 0
	v_mfma_f32_16x16x32_bf16 v[118:121], v[162:165], v[178:181], v[118:121]
	v_mfma_f32_16x16x32_bf16 v[110:113], v[170:173], v[178:181], v[110:113]
	v_mfma_f32_16x16x32_bf16 v[102:105], v[162:165], v[186:189], v[102:105]
	v_mfma_f32_16x16x32_bf16 v[94:97], v[170:173], v[186:189], v[94:97]
	v_mfma_f32_16x16x32_bf16 v[86:89], v[162:165], v[194:197], v[86:89]
	v_mfma_f32_16x16x32_bf16 v[78:81], v[170:173], v[194:197], v[78:81]
	v_mfma_f32_16x16x32_bf16 v[70:73], v[162:165], v[208:211], v[70:73]
	v_mfma_f32_16x16x32_bf16 v[66:69], v[170:173], v[208:211], v[66:69]
	s_setprio 0
	s_barrier
	s_add_i32 s64, s64, s23
	v_lshl_add_u64 v[212:213], s[62:63], 0, v[0:1]
	s_mov_b32 m0, s64
	ds_read_b128 v[174:177], v145 offset:16384
	ds_read_b128 v[178:181], v145 offset:17408
	ds_read_b128 v[182:185], v145 offset:18432
	ds_read_b128 v[186:189], v145 offset:19456
	ds_read_b128 v[190:193], v145 offset:20480
	ds_read_b128 v[194:197], v145 offset:21504
	ds_read_b128 v[198:201], v145 offset:22528
	ds_read_b128 v[208:211], v145 offset:23552
	global_load_lds_dwordx4 v[212:213], off
	s_add_i32 m0, s64, 0x2000
	v_lshl_add_u64 v[214:215], s[62:63], 0, v[134:135]
	s_add_u32 s62, s62, s0
	s_addc_u32 s63, s63, 0
	s_add_i32 s61, s61, s23
	global_load_lds_dwordx4 v[214:215], off
	v_lshl_add_u64 v[216:217], s[62:63], 0, v[0:1]
	s_mov_b32 m0, s61
	v_lshl_add_u64 v[218:219], s[62:63], 0, v[134:135]
	global_load_lds_dwordx4 v[216:217], off
	s_add_i32 m0, s61, 0x2000
	v_lshl_add_u64 v[220:221], s[36:37], 0, v[130:131]
	global_load_lds_dwordx4 v[218:219], off
	s_mov_b32 m0, s42
	v_lshl_add_u64 v[222:223], s[36:37], 0, v[132:133]
	global_load_lds_dwordx4 v[220:221], off
	s_mov_b32 m0, s43
	s_nop 0
	global_load_lds_dwordx4 v[222:223], off
	s_waitcnt vmcnt(8)
	s_waitcnt lgkmcnt(0)
	s_barrier
; #define PG8_STAGE(bufoff, gbase, voff) do { _Pragma("unroll") for (int _i = 0; _i < 2; ++_i) \
;         __builtin_amdgcn_global_load_lds((const unsigned*)((const char*)(gbase) + (voff)[_i]), (LAS unsigned*)(lds + (bufoff) + ldsw + _i * 8192), 16, 0, 0); } while (0)
; #define PG8_LDA(dst, b, h) do { _Pragma("unroll") for (int m = 0; m < 4; ++m) _Pragma("unroll") for (int k = 0; k < 2; ++k) dst[m][k] = *(const LAS bf16x8*)(lds + PG8_SA(b, h) + aoff + m * 2048 + k * 1024); } while (0)
; #define PG8_LDB(dst, b, h) do { _Pragma("unroll") for (int n = 0; n < 2; ++n) _Pragma("unroll") for (int k = 0; k < 2; ++k) dst[n][k] = *(const LAS bf16x8*)(lds + PG8_SB(b, h) + boff + n * 2048 + k * 1024); } while (0)
; #define PG8_MMA(ai, bj, At, Bt) do { __builtin_amdgcn_s_setprio(1); _Pragma("unroll") for (int m = 0; m < 4; ++m) _Pragma("unroll") for (int n = 0; n < 2; ++n) _Pragma("unroll") for (int k = 0; k < 2; ++k) \
;         acc[ai][bj][m][n] = __builtin_amdgcn_mfma_f32_16x16x32_bf16(Bt[n][k], At[m][k], acc[ai][bj][m][n], 0, 0, 0); __builtin_amdgcn_s_setprio(0); } while (0)
; #define PG8_WAIT_V(n) asm volatile("s_waitcnt vmcnt(" #n ")" ::: "memory")
; #define PG8_WAIT_L(n) asm volatile("s_waitcnt lgkmcnt(" #n ")" ::: "memory")
; #define PG8_BAR __builtin_amdgcn_s_barrier()
; #define PG8_SCHED __builtin_amdgcn_sched_barrier(0)
; template <class Epi, bool HALFM = false>
; DI void gemm_phase(LAS unsigned char* lds, const Gemm g, const StaticOrder& S, const Epi& E) {
;     ...
;             PG8_WAIT_V(8); PG8_WAIT_L(0); PG8_BAR; if constexpr (!HALFM) { PG8_MMA(1, 0, At, B0); PG8_MMA(1, 1, At, B1); } PG8_BAR; PG8_SCHED;
;             PG8_LDB(B0, 1, 0); PG8_LDB(B1, 1, 1); PG8_SCHED; PG8_LDA(At, 1, 0); PG8_STAGE(PG8_SA(0, 1), a2 + hstepA, voffA);
;             PG8_WAIT_V(8); PG8_WAIT_L(0); PG8_BAR; PG8_MMA(0, 0, At, B0); PG8_MMA(0, 1, At, B1); PG8_BAR; PG8_SCHED;
	s_setprio 1
	s_waitcnt lgkmcnt(0)
	v_mfma_f32_16x16x32_bf16 v[62:65], v[140:143], v[174:177], 0
	v_mfma_f32_16x16x32_bf16 v[58:61], v[150:153], v[174:177], 0
	v_mfma_f32_16x16x32_bf16 v[50:53], v[140:143], v[182:185], 0
	v_mfma_f32_16x16x32_bf16 v[42:45], v[150:153], v[182:185], 0
	v_mfma_f32_16x16x32_bf16 v[34:37], v[140:143], v[190:193], 0
	v_mfma_f32_16x16x32_bf16 v[26:29], v[150:153], v[190:193], 0
	v_mfma_f32_16x16x32_bf16 v[18:21], v[140:143], v[198:201], 0
	v_mfma_f32_16x16x32_bf16 v[10:13], v[150:153], v[198:201], 0
	v_mfma_f32_16x16x32_bf16 v[62:65], v[146:149], v[178:181], v[62:65]
	v_mfma_f32_16x16x32_bf16 v[58:61], v[154:157], v[178:181], v[58:61]
	v_mfma_f32_16x16x32_bf16 v[50:53], v[146:149], v[186:189], v[50:53]
	v_mfma_f32_16x16x32_bf16 v[42:45], v[154:157], v[186:189], v[42:45]
	v_mfma_f32_16x16x32_bf16 v[34:37], v[146:149], v[194:197], v[34:37]
	v_mfma_f32_16x16x32_bf16 v[26:29], v[154:157], v[194:197], v[26:29]
	v_mfma_f32_16x16x32_bf16 v[18:21], v[146:149], v[208:211], v[18:21]
	v_mfma_f32_16x16x32_bf16 v[10:13], v[154:157], v[208:211], v[10:13]
	s_setprio 0
	s_setprio 1
	v_mfma_f32_16x16x32_bf16 v[54:57], v[158:161], v[174:177], 0
	v_mfma_f32_16x16x32_bf16 v[46:49], v[166:169], v[174:177], 0
	v_mfma_f32_16x16x32_bf16 v[38:41], v[158:161], v[182:185], 0
	v_mfma_f32_16x16x32_bf16 v[30:33], v[166:169], v[182:185], 0
	v_mfma_f32_16x16x32_bf16 v[22:25], v[158:161], v[190:193], 0
	v_mfma_f32_16x16x32_bf16 v[14:17], v[166:169], v[190:193], 0
	v_mfma_f32_16x16x32_bf16 v[6:9], v[158:161], v[198:201], 0
	v_mfma_f32_16x16x32_bf16 v[2:5], v[166:169], v[198:201], 0
	v_mfma_f32_16x16x32_bf16 v[54:57], v[162:165], v[178:181], v[54:57]
	v_mfma_f32_16x16x32_bf16 v[46:49], v[170:173], v[178:181], v[46:49]
	v_mfma_f32_16x16x32_bf16 v[38:41], v[162:165], v[186:189], v[38:41]
	v_mfma_f32_16x16x32_bf16 v[30:33], v[170:173], v[186:189], v[30:33]
	v_mfma_f32_16x16x32_bf16 v[22:25], v[162:165], v[194:197], v[22:25]
	v_mfma_f32_16x16x32_bf16 v[14:17], v[170:173], v[194:197], v[14:17]
	v_mfma_f32_16x16x32_bf16 v[6:9], v[162:165], v[208:211], v[6:9]
	v_mfma_f32_16x16x32_bf16 v[2:5], v[170:173], v[208:211], v[2:5]
	s_setprio 0
	s_barrier
	s_add_i32 s61, s92, 0x100
	s_add_i32 s62, s93, 0x100
	v_add_u32_e32 v154, s61, v144
	v_add_u32_e32 v170, s62, v144
	ds_read_b128 v[140:143], v154
	ds_read_b128 v[146:149], v154 offset:1024
	ds_read_b128 v[150:153], v154 offset:2048
	ds_read_b128 v[154:157], v154 offset:3072
	ds_read_b128 v[158:161], v170
	ds_read_b128 v[162:165], v170 offset:1024
	ds_read_b128 v[166:169], v170 offset:2048
	ds_read_b128 v[170:173], v170 offset:3072
	s_add_u32 s36, s36, s66
	s_addc_u32 s37, s37, 0
	s_mov_b32 m0, s44
	v_lshl_add_u64 v[224:225], s[36:37], 0, v[130:131]
	ds_read_b128 v[174:177], v145 offset:32768
	ds_read_b128 v[178:181], v145 offset:33792
	ds_read_b128 v[182:185], v145 offset:34816
	ds_read_b128 v[186:189], v145 offset:35840
	ds_read_b128 v[190:193], v145 offset:36864
	ds_read_b128 v[194:197], v145 offset:37888
	ds_read_b128 v[198:201], v145 offset:38912
	ds_read_b128 v[208:211], v145 offset:39936
	global_load_lds_dwordx4 v[224:225], off
	v_lshl_add_u64 v[224:225], s[36:37], 0, v[132:133]
	s_mov_b32 m0, s45
	s_nop 0
	global_load_lds_dwordx4 v[224:225], off
	s_waitcnt vmcnt(8)
	s_waitcnt lgkmcnt(0)
	s_barrier
	s_setprio 1
	s_waitcnt lgkmcnt(0)
	v_mfma_f32_16x16x32_bf16 v[126:129], v[140:143], v[174:177], v[126:129]
	v_mfma_f32_16x16x32_bf16 v[122:125], v[150:153], v[174:177], v[122:125]
	v_mfma_f32_16x16x32_bf16 v[114:117], v[140:143], v[182:185], v[114:117]
	v_mfma_f32_16x16x32_bf16 v[106:109], v[150:153], v[182:185], v[106:109]
	v_mfma_f32_16x16x32_bf16 v[98:101], v[140:143], v[190:193], v[98:101]
	v_mfma_f32_16x16x32_bf16 v[90:93], v[150:153], v[190:193], v[90:93]
	v_mfma_f32_16x16x32_bf16 v[82:85], v[140:143], v[198:201], v[82:85]
	v_mfma_f32_16x16x32_bf16 v[74:77], v[150:153], v[198:201], v[74:77]
	v_mfma_f32_16x16x32_bf16 v[126:129], v[146:149], v[178:181], v[126:129]
	v_mfma_f32_16x16x32_bf16 v[122:125], v[154:157], v[178:181], v[122:125]
	v_mfma_f32_16x16x32_bf16 v[114:117], v[146:149], v[186:189], v[114:117]
	v_mfma_f32_16x16x32_bf16 v[106:109], v[154:157], v[186:189], v[106:109]
	v_mfma_f32_16x16x32_bf16 v[98:101], v[146:149], v[194:197], v[98:101]
	v_mfma_f32_16x16x32_bf16 v[90:93], v[154:157], v[194:197], v[90:93]
	v_mfma_f32_16x16x32_bf16 v[82:85], v[146:149], v[208:211], v[82:85]
	v_mfma_f32_16x16x32_bf16 v[74:77], v[154:157], v[208:211], v[74:77]
	s_setprio 0
	s_setprio 1
	v_mfma_f32_16x16x32_bf16 v[118:121], v[158:161], v[174:177], v[118:121]
	v_mfma_f32_16x16x32_bf16 v[110:113], v[166:169], v[174:177], v[110:113]
	v_mfma_f32_16x16x32_bf16 v[102:105], v[158:161], v[182:185], v[102:105]
	v_mfma_f32_16x16x32_bf16 v[94:97], v[166:169], v[182:185], v[94:97]
	v_mfma_f32_16x16x32_bf16 v[86:89], v[158:161], v[190:193], v[86:89]
	v_mfma_f32_16x16x32_bf16 v[78:81], v[166:169], v[190:193], v[78:81]
	v_mfma_f32_16x16x32_bf16 v[70:73], v[158:161], v[198:201], v[70:73]
	v_mfma_f32_16x16x32_bf16 v[66:69], v[166:169], v[198:201], v[66:69]
	v_mfma_f32_16x16x32_bf16 v[118:121], v[162:165], v[178:181], v[118:121]
	v_mfma_f32_16x16x32_bf16 v[110:113], v[170:173], v[178:181], v[110:113]
	v_mfma_f32_16x16x32_bf16 v[102:105], v[162:165], v[186:189], v[102:105]
	v_mfma_f32_16x16x32_bf16 v[94:97], v[170:173], v[186:189], v[94:97]
	v_mfma_f32_16x16x32_bf16 v[86:89], v[162:165], v[194:197], v[86:89]
	v_mfma_f32_16x16x32_bf16 v[78:81], v[170:173], v[194:197], v[78:81]
	v_mfma_f32_16x16x32_bf16 v[70:73], v[162:165], v[208:211], v[70:73]
	v_mfma_f32_16x16x32_bf16 v[66:69], v[170:173], v[208:211], v[66:69]
	s_setprio 0
	s_barrier
; #define PG8_STAGE(bufoff, gbase, voff) do { _Pragma("unroll") for (int _i = 0; _i < 2; ++_i) \
;         __builtin_amdgcn_global_load_lds((const unsigned*)((const char*)(gbase) + (voff)[_i]), (LAS unsigned*)(lds + (bufoff) + ldsw + _i * 8192), 16, 0, 0); } while (0)
; #define PG8_LDA(dst, b, h) do { _Pragma("unroll") for (int m = 0; m < 4; ++m) _Pragma("unroll") for (int k = 0; k < 2; ++k) dst[m][k] = *(const LAS bf16x8*)(lds + PG8_SA(b, h) + aoff + m * 2048 + k * 1024); } while (0)
; #define PG8_MMA(ai, bj, At, Bt) do { __builtin_amdgcn_s_setprio(1); _Pragma("unroll") for (int m = 0; m < 4; ++m) _Pragma("unroll") for (int n = 0; n < 2; ++n) _Pragma("unroll") for (int k = 0; k < 2; ++k) \
;         acc[ai][bj][m][n] = __builtin_amdgcn_mfma_f32_16x16x32_bf16(Bt[n][k], At[m][k], acc[ai][bj][m][n], 0, 0, 0); __builtin_amdgcn_s_setprio(0); } while (0)
; #define PG8_WAIT_V(n) asm volatile("s_waitcnt vmcnt(" #n ")" ::: "memory")
; #define PG8_WAIT_L(n) asm volatile("s_waitcnt lgkmcnt(" #n ")" ::: "memory")
; #define PG8_BAR __builtin_amdgcn_s_barrier()
; #define PG8_SCHED __builtin_amdgcn_sched_barrier(0)
; template <class Epi, bool HALFM = false>
; DI void gemm_phase(LAS unsigned char* lds, const Gemm g, const StaticOrder& S, const Epi& E) {
;     ...
;             if constexpr (!HALFM) PG8_LDA(At, 1, 1);
;             PG8_STAGE(PG8_SB(1, 0), b3, voffB); PG8_STAGE(PG8_SB(1, 1), b3 + hstepB, voffB); PG8_STAGE(PG8_SA(1, 0), a3, voffA);
;             PG8_WAIT_V(8); PG8_WAIT_L(0); PG8_BAR; if constexpr (!HALFM) { PG8_MMA(1, 0, At, B0); PG8_MMA(1, 1, At, B1); } PG8_BAR; PG8_SCHED;
	s_add_i32 s36, s61, s23
	v_lshl_add_u64 v[212:213], v[212:213], 0, s[2:3]
	s_mov_b32 m0, s36
	ds_read_b128 v[174:177], v145 offset:49152
	ds_read_b128 v[178:181], v145 offset:50176
	ds_read_b128 v[182:185], v145 offset:51200
	ds_read_b128 v[186:189], v145 offset:52224
	ds_read_b128 v[190:193], v145 offset:53248
	ds_read_b128 v[194:197], v145 offset:54272
	ds_read_b128 v[198:201], v145 offset:55296
	ds_read_b128 v[208:211], v145 offset:56320
	global_load_lds_dwordx4 v[212:213], off
	v_lshl_add_u64 v[212:213], v[214:215], 0, s[2:3]
	s_add_i32 m0, s36, 0x2000
	s_add_i32 s36, s62, s23
	global_load_lds_dwordx4 v[212:213], off
	v_lshl_add_u64 v[212:213], v[216:217], 0, s[2:3]
	s_mov_b32 m0, s36
	s_nop 0
	global_load_lds_dwordx4 v[212:213], off
	v_lshl_add_u64 v[212:213], v[218:219], 0, s[2:3]
	s_add_i32 m0, s36, 0x2000
	s_nop 0
	global_load_lds_dwordx4 v[212:213], off
	v_lshl_add_u64 v[212:213], v[220:221], 0, s[2:3]
	s_mov_b32 m0, s46
	s_nop 0
	global_load_lds_dwordx4 v[212:213], off
	v_lshl_add_u64 v[212:213], v[222:223], 0, s[2:3]
	s_mov_b32 m0, s47
	s_nop 0
	global_load_lds_dwordx4 v[212:213], off
	s_waitcnt vmcnt(8)
	s_waitcnt lgkmcnt(0)
	s_barrier
	s_setprio 1
	s_waitcnt lgkmcnt(0)
	v_mfma_f32_16x16x32_bf16 v[62:65], v[140:143], v[174:177], v[62:65]
	v_mfma_f32_16x16x32_bf16 v[58:61], v[150:153], v[174:177], v[58:61]
	v_mfma_f32_16x16x32_bf16 v[50:53], v[140:143], v[182:185], v[50:53]
	v_mfma_f32_16x16x32_bf16 v[42:45], v[150:153], v[182:185], v[42:45]
	v_mfma_f32_16x16x32_bf16 v[34:37], v[140:143], v[190:193], v[34:37]
	v_mfma_f32_16x16x32_bf16 v[26:29], v[150:153], v[190:193], v[26:29]
	v_mfma_f32_16x16x32_bf16 v[18:21], v[140:143], v[198:201], v[18:21]
	v_mfma_f32_16x16x32_bf16 v[10:13], v[150:153], v[198:201], v[10:13]
	v_mfma_f32_16x16x32_bf16 v[62:65], v[146:149], v[178:181], v[62:65]
	v_mfma_f32_16x16x32_bf16 v[58:61], v[154:157], v[178:181], v[58:61]
	v_mfma_f32_16x16x32_bf16 v[50:53], v[146:149], v[186:189], v[50:53]
	v_mfma_f32_16x16x32_bf16 v[42:45], v[154:157], v[186:189], v[42:45]
	v_mfma_f32_16x16x32_bf16 v[34:37], v[146:149], v[194:197], v[34:37]
	v_mfma_f32_16x16x32_bf16 v[26:29], v[154:157], v[194:197], v[26:29]
	v_mfma_f32_16x16x32_bf16 v[18:21], v[146:149], v[208:211], v[18:21]
	v_mfma_f32_16x16x32_bf16 v[10:13], v[154:157], v[208:211], v[10:13]
	s_setprio 0
	s_setprio 1
	v_mfma_f32_16x16x32_bf16 v[54:57], v[158:161], v[174:177], v[54:57]
	v_mfma_f32_16x16x32_bf16 v[46:49], v[166:169], v[174:177], v[46:49]
	v_mfma_f32_16x16x32_bf16 v[38:41], v[158:161], v[182:185], v[38:41]
	v_mfma_f32_16x16x32_bf16 v[30:33], v[166:169], v[182:185], v[30:33]
	v_mfma_f32_16x16x32_bf16 v[22:25], v[158:161], v[190:193], v[22:25]
	v_mfma_f32_16x16x32_bf16 v[14:17], v[166:169], v[190:193], v[14:17]
	v_mfma_f32_16x16x32_bf16 v[6:9], v[158:161], v[198:201], v[6:9]
	v_mfma_f32_16x16x32_bf16 v[2:5], v[166:169], v[198:201], v[2:5]
	v_mfma_f32_16x16x32_bf16 v[54:57], v[162:165], v[178:181], v[54:57]
	v_mfma_f32_16x16x32_bf16 v[46:49], v[170:173], v[178:181], v[46:49]
	v_mfma_f32_16x16x32_bf16 v[38:41], v[162:165], v[186:189], v[38:41]
	v_mfma_f32_16x16x32_bf16 v[30:33], v[170:173], v[186:189], v[30:33]
	v_mfma_f32_16x16x32_bf16 v[22:25], v[162:165], v[194:197], v[22:25]
	v_mfma_f32_16x16x32_bf16 v[14:17], v[170:173], v[194:197], v[14:17]
	v_mfma_f32_16x16x32_bf16 v[6:9], v[162:165], v[208:211], v[6:9]
	v_mfma_f32_16x16x32_bf16 v[2:5], v[170:173], v[208:211], v[2:5]
	s_setprio 0
	s_barrier
	s_add_u32 s6, s6, 0x100
	s_addc_u32 s7, s7, 0
	s_add_u32 s38, s38, 0x100
	s_addc_u32 s39, s39, 0
	s_cmp_ge_u32 s60, s48
	s_mov_b32 s36, s60

; #define PG8_STAGE(bufoff, gbase, voff) do { _Pragma("unroll") for (int _i = 0; _i < 2; ++_i) \
;         __builtin_amdgcn_global_load_lds((const unsigned*)((const char*)(gbase) + (voff)[_i]), (LAS unsigned*)(lds + (bufoff) + ldsw + _i * 8192), 16, 0, 0); } while (0)
; #define PG8_LDA(dst, b, h) do { _Pragma("unroll") for (int m = 0; m < 4; ++m) _Pragma("unroll") for (int k = 0; k < 2; ++k) dst[m][k] = *(const LAS bf16x8*)(lds + PG8_SA(b, h) + aoff + m * 2048 + k * 1024); } while (0)
; #define PG8_LDB(dst, b, h) do { _Pragma("unroll") for (int n = 0; n < 2; ++n) _Pragma("unroll") for (int k = 0; k < 2; ++k) dst[n][k] = *(const LAS bf16x8*)(lds + PG8_SB(b, h) + boff + n * 2048 + k * 1024); } while (0)
; #define PG8_MMA(ai, bj, At, Bt) do { __builtin_amdgcn_s_setprio(1); _Pragma("unroll") for (int m = 0; m < 4; ++m) _Pragma("unroll") for (int n = 0; n < 2; ++n) _Pragma("unroll") for (int k = 0; k < 2; ++k) \
;         acc[ai][bj][m][n] = __builtin_amdgcn_mfma_f32_16x16x32_bf16(Bt[n][k], At[m][k], acc[ai][bj][m][n], 0, 0, 0); __builtin_amdgcn_s_setprio(0); } while (0)
; template <class Epi, bool HALFM = false>
; DI void gemm_phase(LAS unsigned char* lds, const Gemm g, const StaticOrder& S, const Epi& E) {
;     ...
; #pragma unroll
;     for (int a = 0; a < 2; ++a)
; #pragma unroll
;         for (int b = 0; b < 2; ++b)
; #pragma unroll
;             for (int m = 0; m < 4; ++m)
; #pragma unroll
;                 for (int n = 0; n < 2; ++n) acc[a][b][m][n] = (f32x4){0.f, 0.f, 0.f, 0.f};
;     ...
;             const bool last = (t == nt - 2);
;             const char* a1 = cA + (size_t)(t + 1) * kstep;
;             const char* a2 = last ? nA : cA + (size_t)(t + 2) * kstep; const char* b2 = last ? nB : cB + (size_t)(t + 2) * kstep;
;             const char* a3 = a2 + kstep; const char* b3 = b2 + kstep;
;             PG8_LDB(B0, 0, 0); PG8_LDB(B1, 0, 1); PG8_SCHED; PG8_LDA(At, 0, 0); PG8_STAGE(PG8_SA(1, 1), a1 + hstepA, voffA);
;             PG8_WAIT_V(8); PG8_WAIT_L(0); PG8_BAR; PG8_MMA(0, 0, At, B0); PG8_MMA(0, 1, At, B1); PG8_BAR; PG8_SCHED;
;             if constexpr (!HALFM) PG8_LDA(At, 0, 1);
;             PG8_STAGE(PG8_SB(0, 0), b2, voffB); PG8_STAGE(PG8_SB(0, 1), b2 + hstepB, voffB); PG8_STAGE(PG8_SA(0, 0), a2, voffA);
;             PG8_WAIT_V(8); PG8_WAIT_L(0); PG8_BAR; if constexpr (!HALFM) { PG8_MMA(1, 0, At, B0); PG8_MMA(1, 1, At, B1); } PG8_BAR; PG8_SCHED;
.LBB0_604:
	s_ashr_i32 s17, s16, 31
	s_lshl_b64 s[4:5], s[16:17], 19
	v_readlane_b32 s20, v254, 63
	v_readlane_b32 s21, v255, 0
	s_add_u32 s20, s20, s4
	s_addc_u32 s21, s21, s5
	s_and_b64 s[4:5], s[8:9], exec
	s_cselect_b32 s4, s21, s25
	s_cselect_b32 s5, s20, s24
	s_ashr_i32 s15, s14, 31
	s_lshl_b64 s[22:23], s[14:15], 19
	s_add_u32 s22, s30, s22
	s_addc_u32 s23, s31, s23
	s_and_b64 s[28:29], s[8:9], exec
	s_cselect_b32 s15, s23, s27
	s_cselect_b32 s17, s22, s26
	s_add_u32 s24, s24, 0x40080
	s_addc_u32 s25, s25, 0
	s_add_u32 s33, s26, 0x100
	s_addc_u32 s44, s27, 0
	s_mov_b32 s45, -2
	s_add_u32 s26, s24, 0xfffc0080
	s_addc_u32 s27, s25, -1
	s_add_i32 s46, s90, 0x100
	s_cmp_eq_u32 s45, 12
	s_cselect_b32 s29, s4, s27
	s_cselect_b32 s28, s5, s26
	s_cselect_b32 s27, s15, s44
	s_cselect_b32 s26, s17, s33
	s_add_i32 s48, s91, 0x100
	v_add_u32_e32 v154, s46, v144
	v_add_u32_e32 v170, s48, v144
	ds_read_b128 v[140:143], v154
	ds_read_b128 v[146:149], v154 offset:1024
	ds_read_b128 v[150:153], v154 offset:2048
	ds_read_b128 v[154:157], v154 offset:3072
	ds_read_b128 v[158:161], v170
	ds_read_b128 v[162:165], v170 offset:1024
	ds_read_b128 v[166:169], v170 offset:2048
	ds_read_b128 v[170:173], v170 offset:3072
	v_lshl_add_u64 v[212:213], s[24:25], 0, v[136:137]
	s_add_i32 m0, s35, 0xc000
	ds_read_b128 v[174:177], v145
	ds_read_b128 v[178:181], v145 offset:1024
	ds_read_b128 v[182:185], v145 offset:2048
	ds_read_b128 v[186:189], v145 offset:3072
	ds_read_b128 v[190:193], v145 offset:4096
	ds_read_b128 v[194:197], v145 offset:5120
	ds_read_b128 v[198:201], v145 offset:6144
	ds_read_b128 v[208:211], v145 offset:7168
	global_load_lds_dwordx4 v[212:213], off
	v_lshl_add_u64 v[212:213], s[24:25], 0, v[138:139]
	s_add_i32 m0, s35, 0xe000
	s_nop 0
	global_load_lds_dwordx4 v[212:213], off
	s_waitcnt vmcnt(8)
	s_waitcnt lgkmcnt(0)
	s_barrier
	s_setprio 1
	s_waitcnt lgkmcnt(0)
	v_mfma_f32_16x16x32_bf16 v[126:129], v[140:143], v[174:177], 0
	v_mfma_f32_16x16x32_bf16 v[122:125], v[150:153], v[174:177], 0
	v_mfma_f32_16x16x32_bf16 v[110:113], v[140:143], v[182:185], 0
	v_mfma_f32_16x16x32_bf16 v[102:105], v[150:153], v[182:185], 0
	v_mfma_f32_16x16x32_bf16 v[94:97], v[140:143], v[190:193], 0
	v_mfma_f32_16x16x32_bf16 v[86:89], v[150:153], v[190:193], 0
	v_mfma_f32_16x16x32_bf16 v[78:81], v[140:143], v[198:201], 0
	v_mfma_f32_16x16x32_bf16 v[70:73], v[150:153], v[198:201], 0
	v_mfma_f32_16x16x32_bf16 v[126:129], v[146:149], v[178:181], v[126:129]
	v_mfma_f32_16x16x32_bf16 v[122:125], v[154:157], v[178:181], v[122:125]
	v_mfma_f32_16x16x32_bf16 v[110:113], v[146:149], v[186:189], v[110:113]
	v_mfma_f32_16x16x32_bf16 v[102:105], v[154:157], v[186:189], v[102:105]
	v_mfma_f32_16x16x32_bf16 v[94:97], v[146:149], v[194:197], v[94:97]
	v_mfma_f32_16x16x32_bf16 v[86:89], v[154:157], v[194:197], v[86:89]
	v_mfma_f32_16x16x32_bf16 v[78:81], v[146:149], v[208:211], v[78:81]
	v_mfma_f32_16x16x32_bf16 v[70:73], v[154:157], v[208:211], v[70:73]
	s_setprio 0
	s_setprio 1
	v_mfma_f32_16x16x32_bf16 v[118:121], v[158:161], v[174:177], 0
	v_mfma_f32_16x16x32_bf16 v[114:117], v[166:169], v[174:177], 0
	v_mfma_f32_16x16x32_bf16 v[106:109], v[158:161], v[182:185], 0
	v_mfma_f32_16x16x32_bf16 v[98:101], v[166:169], v[182:185], 0
	v_mfma_f32_16x16x32_bf16 v[90:93], v[158:161], v[190:193], 0
	v_mfma_f32_16x16x32_bf16 v[82:85], v[166:169], v[190:193], 0
	v_mfma_f32_16x16x32_bf16 v[74:77], v[158:161], v[198:201], 0
	v_mfma_f32_16x16x32_bf16 v[66:69], v[166:169], v[198:201], 0
	v_mfma_f32_16x16x32_bf16 v[118:121], v[162:165], v[178:181], v[118:121]
	v_mfma_f32_16x16x32_bf16 v[114:117], v[170:173], v[178:181], v[114:117]
	v_mfma_f32_16x16x32_bf16 v[106:109], v[162:165], v[186:189], v[106:109]
	v_mfma_f32_16x16x32_bf16 v[98:101], v[170:173], v[186:189], v[98:101]
	v_mfma_f32_16x16x32_bf16 v[90:93], v[162:165], v[194:197], v[90:93]
	v_mfma_f32_16x16x32_bf16 v[82:85], v[170:173], v[194:197], v[82:85]
	v_mfma_f32_16x16x32_bf16 v[74:77], v[162:165], v[208:211], v[74:77]
	v_mfma_f32_16x16x32_bf16 v[66:69], v[170:173], v[208:211], v[66:69]
	s_setprio 0
	s_barrier
	s_add_i32 s46, s46, s34
	v_lshl_add_u64 v[212:213], s[26:27], 0, v[0:1]
	s_mov_b32 m0, s46
	ds_read_b128 v[174:177], v145 offset:16384
	ds_read_b128 v[178:181], v145 offset:17408
	ds_read_b128 v[182:185], v145 offset:18432
	ds_read_b128 v[186:189], v145 offset:19456
	ds_read_b128 v[190:193], v145 offset:20480
	ds_read_b128 v[194:197], v145 offset:21504
	ds_read_b128 v[198:201], v145 offset:22528
	ds_read_b128 v[208:211], v145 offset:23552
	global_load_lds_dwordx4 v[212:213], off
	s_add_i32 m0, s46, 0x2000
	s_add_u32 s46, s26, 0x40000
	v_lshl_add_u64 v[214:215], s[26:27], 0, v[130:131]
	s_addc_u32 s47, s27, 0
	s_add_i32 s48, s48, s34
	global_load_lds_dwordx4 v[214:215], off
	v_lshl_add_u64 v[216:217], s[46:47], 0, v[0:1]
	s_mov_b32 m0, s48
	v_lshl_add_u64 v[218:219], s[28:29], 0, v[132:133]
	global_load_lds_dwordx4 v[216:217], off
	v_lshl_add_u64 v[216:217], s[46:47], 0, v[130:131]
	s_add_i32 m0, s48, 0x2000
	s_nop 0
	global_load_lds_dwordx4 v[216:217], off
	v_lshl_add_u64 v[216:217], s[28:29], 0, v[134:135]
	s_mov_b32 m0, s35
	s_nop 0
	global_load_lds_dwordx4 v[216:217], off
	s_mov_b32 m0, s36
	s_nop 0
	global_load_lds_dwordx4 v[218:219], off
	s_waitcnt vmcnt(8)
	s_waitcnt lgkmcnt(0)
	s_barrier
; #define PG8_STAGE(bufoff, gbase, voff) do { _Pragma("unroll") for (int _i = 0; _i < 2; ++_i) \
;         __builtin_amdgcn_global_load_lds((const unsigned*)((const char*)(gbase) + (voff)[_i]), (LAS unsigned*)(lds + (bufoff) + ldsw + _i * 8192), 16, 0, 0); } while (0)
; #define PG8_LDA(dst, b, h) do { _Pragma("unroll") for (int m = 0; m < 4; ++m) _Pragma("unroll") for (int k = 0; k < 2; ++k) dst[m][k] = *(const LAS bf16x8*)(lds + PG8_SA(b, h) + aoff + m * 2048 + k * 1024); } while (0)
; #define PG8_LDB(dst, b, h) do { _Pragma("unroll") for (int n = 0; n < 2; ++n) _Pragma("unroll") for (int k = 0; k < 2; ++k) dst[n][k] = *(const LAS bf16x8*)(lds + PG8_SB(b, h) + boff + n * 2048 + k * 1024); } while (0)
; #define PG8_MMA(ai, bj, At, Bt) do { __builtin_amdgcn_s_setprio(1); _Pragma("unroll") for (int m = 0; m < 4; ++m) _Pragma("unroll") for (int n = 0; n < 2; ++n) _Pragma("unroll") for (int k = 0; k < 2; ++k) \
;         acc[ai][bj][m][n] = __builtin_amdgcn_mfma_f32_16x16x32_bf16(Bt[n][k], At[m][k], acc[ai][bj][m][n], 0, 0, 0); __builtin_amdgcn_s_setprio(0); } while (0)
; #define PG8_WAIT_V(n) asm volatile("s_waitcnt vmcnt(" #n ")" ::: "memory")
; #define PG8_WAIT_L(n) asm volatile("s_waitcnt lgkmcnt(" #n ")" ::: "memory")
; #define PG8_BAR __builtin_amdgcn_s_barrier()
; #define PG8_SCHED __builtin_amdgcn_sched_barrier(0)
; template <class Epi, bool HALFM = false>
; DI void gemm_phase(LAS unsigned char* lds, const Gemm g, const StaticOrder& S, const Epi& E) {
;     ...
;             PG8_WAIT_V(8); PG8_WAIT_L(0); PG8_BAR; if constexpr (!HALFM) { PG8_MMA(1, 0, At, B0); PG8_MMA(1, 1, At, B1); } PG8_BAR; PG8_SCHED;
;             PG8_LDB(B0, 1, 0); PG8_LDB(B1, 1, 1); PG8_SCHED; PG8_LDA(At, 1, 0); PG8_STAGE(PG8_SA(0, 1), a2 + hstepA, voffA);
;             PG8_WAIT_V(8); PG8_WAIT_L(0); PG8_BAR; PG8_MMA(0, 0, At, B0); PG8_MMA(0, 1, At, B1); PG8_BAR; PG8_SCHED;
	s_setprio 1
	s_waitcnt lgkmcnt(0)
	v_mfma_f32_16x16x32_bf16 v[62:65], v[140:143], v[174:177], 0
	v_mfma_f32_16x16x32_bf16 v[54:57], v[150:153], v[174:177], 0
	v_mfma_f32_16x16x32_bf16 v[46:49], v[140:143], v[182:185], 0
	v_mfma_f32_16x16x32_bf16 v[38:41], v[150:153], v[182:185], 0
	v_mfma_f32_16x16x32_bf16 v[30:33], v[140:143], v[190:193], 0
	v_mfma_f32_16x16x32_bf16 v[22:25], v[150:153], v[190:193], 0
	v_mfma_f32_16x16x32_bf16 v[14:17], v[140:143], v[198:201], 0
	v_mfma_f32_16x16x32_bf16 v[6:9], v[150:153], v[198:201], 0
	v_mfma_f32_16x16x32_bf16 v[62:65], v[146:149], v[178:181], v[62:65]
	v_mfma_f32_16x16x32_bf16 v[54:57], v[154:157], v[178:181], v[54:57]
	v_mfma_f32_16x16x32_bf16 v[46:49], v[146:149], v[186:189], v[46:49]
	v_mfma_f32_16x16x32_bf16 v[38:41], v[154:157], v[186:189], v[38:41]
	v_mfma_f32_16x16x32_bf16 v[30:33], v[146:149], v[194:197], v[30:33]
	v_mfma_f32_16x16x32_bf16 v[22:25], v[154:157], v[194:197], v[22:25]
	v_mfma_f32_16x16x32_bf16 v[14:17], v[146:149], v[208:211], v[14:17]
	v_mfma_f32_16x16x32_bf16 v[6:9], v[154:157], v[208:211], v[6:9]
	s_setprio 0
	s_setprio 1
	v_mfma_f32_16x16x32_bf16 v[58:61], v[158:161], v[174:177], 0
	v_mfma_f32_16x16x32_bf16 v[50:53], v[166:169], v[174:177], 0
	v_mfma_f32_16x16x32_bf16 v[42:45], v[158:161], v[182:185], 0
	v_mfma_f32_16x16x32_bf16 v[34:37], v[166:169], v[182:185], 0
	v_mfma_f32_16x16x32_bf16 v[26:29], v[158:161], v[190:193], 0
	v_mfma_f32_16x16x32_bf16 v[18:21], v[166:169], v[190:193], 0
	v_mfma_f32_16x16x32_bf16 v[10:13], v[158:161], v[198:201], 0
	v_mfma_f32_16x16x32_bf16 v[2:5], v[166:169], v[198:201], 0
	v_mfma_f32_16x16x32_bf16 v[58:61], v[162:165], v[178:181], v[58:61]
	v_mfma_f32_16x16x32_bf16 v[50:53], v[170:173], v[178:181], v[50:53]
	v_mfma_f32_16x16x32_bf16 v[42:45], v[162:165], v[186:189], v[42:45]
	v_mfma_f32_16x16x32_bf16 v[34:37], v[170:173], v[186:189], v[34:37]
	v_mfma_f32_16x16x32_bf16 v[26:29], v[162:165], v[194:197], v[26:29]
	v_mfma_f32_16x16x32_bf16 v[18:21], v[170:173], v[194:197], v[18:21]
	v_mfma_f32_16x16x32_bf16 v[10:13], v[162:165], v[208:211], v[10:13]
	v_mfma_f32_16x16x32_bf16 v[2:5], v[170:173], v[208:211], v[2:5]
	s_setprio 0
	s_barrier
	s_add_i32 s46, s92, 0x100
	s_add_i32 s47, s93, 0x100
	v_add_u32_e32 v154, s46, v144
	v_add_u32_e32 v170, s47, v144
	ds_read_b128 v[140:143], v154
	ds_read_b128 v[146:149], v154 offset:1024
	ds_read_b128 v[150:153], v154 offset:2048
	ds_read_b128 v[154:157], v154 offset:3072
	ds_read_b128 v[158:161], v170
	ds_read_b128 v[162:165], v170 offset:1024
	ds_read_b128 v[166:169], v170 offset:2048
	ds_read_b128 v[170:173], v170 offset:3072
	s_add_u32 s28, s28, 0x40000
	s_addc_u32 s29, s29, 0
	s_mov_b32 m0, s37
	v_lshl_add_u64 v[220:221], s[28:29], 0, v[134:135]
	ds_read_b128 v[174:177], v145 offset:32768
	ds_read_b128 v[178:181], v145 offset:33792
	ds_read_b128 v[182:185], v145 offset:34816
	ds_read_b128 v[186:189], v145 offset:35840
	ds_read_b128 v[190:193], v145 offset:36864
	ds_read_b128 v[194:197], v145 offset:37888
	ds_read_b128 v[198:201], v145 offset:38912
	ds_read_b128 v[208:211], v145 offset:39936
	global_load_lds_dwordx4 v[220:221], off
	v_lshl_add_u64 v[220:221], s[28:29], 0, v[132:133]
	s_mov_b32 m0, s38
	s_nop 0
	global_load_lds_dwordx4 v[220:221], off
	s_waitcnt vmcnt(8)
	s_waitcnt lgkmcnt(0)
	s_barrier
	s_setprio 1
	s_waitcnt lgkmcnt(0)
	v_mfma_f32_16x16x32_bf16 v[126:129], v[140:143], v[174:177], v[126:129]
	v_mfma_f32_16x16x32_bf16 v[122:125], v[150:153], v[174:177], v[122:125]
	v_mfma_f32_16x16x32_bf16 v[110:113], v[140:143], v[182:185], v[110:113]
	v_mfma_f32_16x16x32_bf16 v[102:105], v[150:153], v[182:185], v[102:105]
	v_mfma_f32_16x16x32_bf16 v[94:97], v[140:143], v[190:193], v[94:97]
	v_mfma_f32_16x16x32_bf16 v[86:89], v[150:153], v[190:193], v[86:89]
	v_mfma_f32_16x16x32_bf16 v[78:81], v[140:143], v[198:201], v[78:81]
	v_mfma_f32_16x16x32_bf16 v[70:73], v[150:153], v[198:201], v[70:73]
	v_mfma_f32_16x16x32_bf16 v[126:129], v[146:149], v[178:181], v[126:129]
	v_mfma_f32_16x16x32_bf16 v[122:125], v[154:157], v[178:181], v[122:125]
	v_mfma_f32_16x16x32_bf16 v[110:113], v[146:149], v[186:189], v[110:113]
	v_mfma_f32_16x16x32_bf16 v[102:105], v[154:157], v[186:189], v[102:105]
	v_mfma_f32_16x16x32_bf16 v[94:97], v[146:149], v[194:197], v[94:97]
	v_mfma_f32_16x16x32_bf16 v[86:89], v[154:157], v[194:197], v[86:89]
	v_mfma_f32_16x16x32_bf16 v[78:81], v[146:149], v[208:211], v[78:81]
	v_mfma_f32_16x16x32_bf16 v[70:73], v[154:157], v[208:211], v[70:73]
	s_setprio 0
	s_setprio 1
	v_mfma_f32_16x16x32_bf16 v[118:121], v[158:161], v[174:177], v[118:121]
	v_mfma_f32_16x16x32_bf16 v[114:117], v[166:169], v[174:177], v[114:117]
	v_mfma_f32_16x16x32_bf16 v[106:109], v[158:161], v[182:185], v[106:109]
	v_mfma_f32_16x16x32_bf16 v[98:101], v[166:169], v[182:185], v[98:101]
	v_mfma_f32_16x16x32_bf16 v[90:93], v[158:161], v[190:193], v[90:93]
	v_mfma_f32_16x16x32_bf16 v[82:85], v[166:169], v[190:193], v[82:85]
	v_mfma_f32_16x16x32_bf16 v[74:77], v[158:161], v[198:201], v[74:77]
	v_mfma_f32_16x16x32_bf16 v[66:69], v[166:169], v[198:201], v[66:69]
	v_mfma_f32_16x16x32_bf16 v[118:121], v[162:165], v[178:181], v[118:121]
	v_mfma_f32_16x16x32_bf16 v[114:117], v[170:173], v[178:181], v[114:117]
	v_mfma_f32_16x16x32_bf16 v[106:109], v[162:165], v[186:189], v[106:109]
	v_mfma_f32_16x16x32_bf16 v[98:101], v[170:173], v[186:189], v[98:101]
	v_mfma_f32_16x16x32_bf16 v[90:93], v[162:165], v[194:197], v[90:93]
	v_mfma_f32_16x16x32_bf16 v[82:85], v[170:173], v[194:197], v[82:85]
	v_mfma_f32_16x16x32_bf16 v[74:77], v[162:165], v[208:211], v[74:77]
	v_mfma_f32_16x16x32_bf16 v[66:69], v[170:173], v[208:211], v[66:69]
	s_setprio 0
	s_barrier
; #define PG8_STAGE(bufoff, gbase, voff) do { _Pragma("unroll") for (int _i = 0; _i < 2; ++_i) \
;         __builtin_amdgcn_global_load_lds((const unsigned*)((const char*)(gbase) + (voff)[_i]), (LAS unsigned*)(lds + (bufoff) + ldsw + _i * 8192), 16, 0, 0); } while (0)
; #define PG8_LDA(dst, b, h) do { _Pragma("unroll") for (int m = 0; m < 4; ++m) _Pragma("unroll") for (int k = 0; k < 2; ++k) dst[m][k] = *(const LAS bf16x8*)(lds + PG8_SA(b, h) + aoff + m * 2048 + k * 1024); } while (0)
; #define PG8_MMA(ai, bj, At, Bt) do { __builtin_amdgcn_s_setprio(1); _Pragma("unroll") for (int m = 0; m < 4; ++m) _Pragma("unroll") for (int n = 0; n < 2; ++n) _Pragma("unroll") for (int k = 0; k < 2; ++k) \
;         acc[ai][bj][m][n] = __builtin_amdgcn_mfma_f32_16x16x32_bf16(Bt[n][k], At[m][k], acc[ai][bj][m][n], 0, 0, 0); __builtin_amdgcn_s_setprio(0); } while (0)
; #define PG8_WAIT_V(n) asm volatile("s_waitcnt vmcnt(" #n ")" ::: "memory")
; #define PG8_WAIT_L(n) asm volatile("s_waitcnt lgkmcnt(" #n ")" ::: "memory")
; #define PG8_BAR __builtin_amdgcn_s_barrier()
; #define PG8_SCHED __builtin_amdgcn_sched_barrier(0)
; template <class Epi, bool HALFM = false>
; DI void gemm_phase(LAS unsigned char* lds, const Gemm g, const StaticOrder& S, const Epi& E) {
;     ...
;             if constexpr (!HALFM) PG8_LDA(At, 1, 1);
;             PG8_STAGE(PG8_SB(1, 0), b3, voffB); PG8_STAGE(PG8_SB(1, 1), b3 + hstepB, voffB); PG8_STAGE(PG8_SA(1, 0), a3, voffA);
;             PG8_WAIT_V(8); PG8_WAIT_L(0); PG8_BAR; if constexpr (!HALFM) { PG8_MMA(1, 0, At, B0); PG8_MMA(1, 1, At, B1); } PG8_BAR; PG8_SCHED;
	s_add_i32 s28, s46, s34
	v_lshl_add_u64 v[212:213], v[212:213], 0, s[2:3]
	s_mov_b32 m0, s28
	ds_read_b128 v[174:177], v145 offset:49152
	ds_read_b128 v[178:181], v145 offset:50176
	ds_read_b128 v[182:185], v145 offset:51200
	ds_read_b128 v[186:189], v145 offset:52224
	ds_read_b128 v[190:193], v145 offset:53248
	ds_read_b128 v[194:197], v145 offset:54272
	ds_read_b128 v[198:201], v145 offset:55296
	ds_read_b128 v[208:211], v145 offset:56320
	global_load_lds_dwordx4 v[212:213], off
	s_add_i32 m0, s28, 0x2000
	s_add_u32 s26, s26, 0x40080
	v_lshl_add_u64 v[212:213], v[214:215], 0, s[2:3]
	s_addc_u32 s27, s27, 0
	s_add_i32 s28, s47, s34
	global_load_lds_dwordx4 v[212:213], off
	v_lshl_add_u64 v[212:213], s[26:27], 0, v[0:1]
	s_mov_b32 m0, s28
	s_nop 0
	global_load_lds_dwordx4 v[212:213], off
	v_lshl_add_u64 v[212:213], s[26:27], 0, v[130:131]
	s_add_i32 m0, s28, 0x2000
	s_nop 0
	global_load_lds_dwordx4 v[212:213], off
	v_lshl_add_u64 v[212:213], v[216:217], 0, s[2:3]
	s_mov_b32 m0, s41
	s_nop 0
	global_load_lds_dwordx4 v[212:213], off
	v_lshl_add_u64 v[212:213], v[218:219], 0, s[2:3]
	s_mov_b32 m0, s42
	s_nop 0
	global_load_lds_dwordx4 v[212:213], off
	s_waitcnt vmcnt(8)
	s_waitcnt lgkmcnt(0)
	s_barrier
	s_setprio 1
	s_waitcnt lgkmcnt(0)
	v_mfma_f32_16x16x32_bf16 v[62:65], v[140:143], v[174:177], v[62:65]
	v_mfma_f32_16x16x32_bf16 v[54:57], v[150:153], v[174:177], v[54:57]
	v_mfma_f32_16x16x32_bf16 v[46:49], v[140:143], v[182:185], v[46:49]
	v_mfma_f32_16x16x32_bf16 v[38:41], v[150:153], v[182:185], v[38:41]
	v_mfma_f32_16x16x32_bf16 v[30:33], v[140:143], v[190:193], v[30:33]
	v_mfma_f32_16x16x32_bf16 v[22:25], v[150:153], v[190:193], v[22:25]
	v_mfma_f32_16x16x32_bf16 v[14:17], v[140:143], v[198:201], v[14:17]
	v_mfma_f32_16x16x32_bf16 v[6:9], v[150:153], v[198:201], v[6:9]
	v_mfma_f32_16x16x32_bf16 v[62:65], v[146:149], v[178:181], v[62:65]
	v_mfma_f32_16x16x32_bf16 v[54:57], v[154:157], v[178:181], v[54:57]
	v_mfma_f32_16x16x32_bf16 v[46:49], v[146:149], v[186:189], v[46:49]
	v_mfma_f32_16x16x32_bf16 v[38:41], v[154:157], v[186:189], v[38:41]
	v_mfma_f32_16x16x32_bf16 v[30:33], v[146:149], v[194:197], v[30:33]
	v_mfma_f32_16x16x32_bf16 v[22:25], v[154:157], v[194:197], v[22:25]
	v_mfma_f32_16x16x32_bf16 v[14:17], v[146:149], v[208:211], v[14:17]
	v_mfma_f32_16x16x32_bf16 v[6:9], v[154:157], v[208:211], v[6:9]
	s_setprio 0
	s_setprio 1
	v_mfma_f32_16x16x32_bf16 v[58:61], v[158:161], v[174:177], v[58:61]
	v_mfma_f32_16x16x32_bf16 v[50:53], v[166:169], v[174:177], v[50:53]
	v_mfma_f32_16x16x32_bf16 v[42:45], v[158:161], v[182:185], v[42:45]
	v_mfma_f32_16x16x32_bf16 v[34:37], v[166:169], v[182:185], v[34:37]
	v_mfma_f32_16x16x32_bf16 v[26:29], v[158:161], v[190:193], v[26:29]
	v_mfma_f32_16x16x32_bf16 v[18:21], v[166:169], v[190:193], v[18:21]
	v_mfma_f32_16x16x32_bf16 v[10:13], v[158:161], v[198:201], v[10:13]
	v_mfma_f32_16x16x32_bf16 v[2:5], v[166:169], v[198:201], v[2:5]
	v_mfma_f32_16x16x32_bf16 v[58:61], v[162:165], v[178:181], v[58:61]
	v_mfma_f32_16x16x32_bf16 v[50:53], v[170:173], v[178:181], v[50:53]
	v_mfma_f32_16x16x32_bf16 v[42:45], v[162:165], v[186:189], v[42:45]
	v_mfma_f32_16x16x32_bf16 v[34:37], v[170:173], v[186:189], v[34:37]
	v_mfma_f32_16x16x32_bf16 v[26:29], v[162:165], v[194:197], v[26:29]
	v_mfma_f32_16x16x32_bf16 v[18:21], v[170:173], v[194:197], v[18:21]
	v_mfma_f32_16x16x32_bf16 v[10:13], v[162:165], v[208:211], v[10:13]
	v_mfma_f32_16x16x32_bf16 v[2:5], v[170:173], v[208:211], v[2:5]
	s_setprio 0
	s_barrier
	s_add_i32 s45, s45, 2
	s_add_u32 s24, s24, 0x100
	s_addc_u32 s25, s25, 0
	s_add_u32 s33, s33, 0x100
	s_addc_u32 s44, s44, 0
	s_cmp_gt_u32 s45, 13
